# 4-buffer attention loop (K/V tiles by LDS-DMA 3 tiles ahead, scan loads 4 tiles ahead) + batched-load epilogues for out-proj, FFN-out and attention units
# speedup vs baseline: 1.1105x; 1.0208x over previous
.LBB0_424:
	s_and_b64 vcc, exec, s[2:3]
	s_cbranch_vccz .LBB0_448
	s_ashr_i32 s18, s33, 3
	v_mov_b32_e32 v0, v188
	s_cmpk_gt_i32 s18, 0x7f
	s_cbranch_scc1 .LBB0_448
	v_lshl_add_u32 v1, s33, 9, v0
	v_ashrrev_i32_e32 v2, 12, v1
	v_and_b32_e32 v5, 63, v0
	v_mul_i32_i24_e32 v0, 0x84, v2
	v_bfe_u32 v4, v1, 6, 6
	v_ashrrev_i32_e32 v1, 31, v0
	v_lshlrev_b64 v[2:3], 14, v[0:1]
	v_lshl_add_u64 v[2:3], s[74:75], 0, v[2:3]
	v_lshlrev_b32_e32 v166, 8, v4
	v_mov_b32_e32 v167, 0
	v_exp_f32_e32 v16, 0xf149f2ca
	v_lshl_add_u64 v[2:3], v[2:3], 0, v[166:167]
	v_lshlrev_b32_e32 v166, 2, v5
	v_lshlrev_b64 v[0:1], 8, v[0:1]
	v_lshl_add_u64 v[2:3], v[2:3], 0, v[166:167]
	s_mov_b64 s[0:1], 0xa085000
	v_lshl_add_u64 v[0:1], s[74:75], 0, v[0:1]
	v_lshlrev_b32_e32 v166, 2, v4
	v_lshl_add_u64 v[168:169], v[2:3], 0, s[0:1]
	v_lshl_add_u64 v[0:1], v[0:1], 0, v[166:167]
	s_mov_b64 s[0:1], 0x5d000
	v_lshl_add_u64 v[170:171], v[0:1], 0, s[0:1]
	s_lshl_b32 s0, s33, 1
	v_add_f32_e32 v17, v16, v16
	s_and_b32 s19, s0, 14
	v_fma_f32 v18, 2.0, v16, v17
	s_add_u32 s8, s74, 0xe285000
	v_fmac_f32_e32 v18, 2.0, v17
	v_cvt_pk_bf16_f32 v128, v16, v16
	v_mbcnt_lo_u32_b32 v16, -1, 0
	s_addc_u32 s9, s75, 0
	v_fmac_f32_e32 v18, 2.0, v17
	v_mbcnt_hi_u32_b32 v190, -1, v16
	s_add_u32 s10, s74, 0x23000
	s_waitcnt vmcnt(0)
	v_xor_b32_e32 v0, 0x80000000, v165
	v_fmac_f32_e32 v18, 2.0, v17
	v_and_b32_e32 v16, 64, v190
	s_addc_u32 s11, s75, 0
	v_mov_b32_e32 v1, v0
	v_mov_b32_e32 v2, v0
	v_mov_b32_e32 v3, v0
	v_mov_b32_e32 v4, v0
	v_mov_b32_e32 v5, v0
	v_mov_b32_e32 v6, v0
	v_mov_b32_e32 v7, v0
	v_mov_b32_e32 v8, v0
	v_mov_b32_e32 v9, v0
	v_mov_b32_e32 v10, v0
	v_mov_b32_e32 v11, v0
	v_mov_b32_e32 v12, v0
	v_mov_b32_e32 v13, v0
	v_mov_b32_e32 v14, v0
	v_mov_b32_e32 v15, v0
	v_add_f32_e32 v165, 0, v18
	v_mov_b32_e32 v129, v128
	v_mov_b32_e32 v130, v128
	v_mov_b32_e32 v131, v128
	s_mov_b32 s13, 0
	s_movk_i32 s20, 0x1a00
	v_mov_b64_e32 v[172:173], s[8:9]
	v_mov_b32_e32 v189, 0x1a00
	v_xor_b32_e32 v191, 32, v190
	v_add_u32_e32 v192, 64, v16
	s_movk_i32 s21, 0x500
	s_add_i32 s22, 0, 0x16c00
	s_movk_i32 s23, 0x2ff
	s_movk_i32 s24, 0x140
	s_movk_i32 s25, 0x1000
	s_movk_i32 s26, 0x110
	v_mov_b32_e32 v193, 0x358637bd
	s_mov_b32 s27, 0x800000
	s_add_i32 s28, 0, 0x12800
	s_mov_b64 s[14:15], 0x6085400
	s_mov_b32 s29, 0x6085000
	v_mov_b32_e32 v226, v167
	v_mov_b32_e32 v227, v167
	v_mov_b32_e32 v228, v167
	v_mov_b32_e32 v229, v167
	s_mov_b32 s35, 0
	v_mov_b32_e32 v174, v167
	v_mov_b32_e32 v194, 0
	v_mov_b32_e32 v182, v167
	v_mov_b32_e32 v183, v167
	v_cvt_pk_bf16_f32 v206, v182, v183
	global_load_dword v194, v[168:169], off
	global_load_dword v174, v[170:171], off
	global_store_dword v[168:169], v206, off
	s_branch .LBB0_428
.LBB0_427:
	v_mov_b32_e32 v189, 0x1a00
	v_xor_b32_e32 v191, 32, v190
	v_and_b32_e32 v192, 64, v190
	v_add_u32_e32 v192, 64, v192
	s_add_i32 s0, s18, 32
	s_cmpk_gt_i32 s18, 0x5f
	s_mov_b32 s18, s0
	s_barrier
	s_cbranch_scc1 .LBB0_448
.LBB0_428:
	s_ashr_i32 s0, s18, 6
	s_add_i32 s4, s0, s19
	s_ashr_i32 s16, s4, 2
	v_mov_b32_e32 v132, v188
	s_ashr_i32 s17, s16, 31
	v_readfirstlane_b32 s34, v132
	s_lshl_b32 s5, s18, 7
	s_bfe_u32 s31, s34, 0x20006
	s_lshl_b64 s[2:3], s[16:17], 13
	s_and_b32 s0, s5, 0x1f80
	s_or_b32 s0, s2, s0
	s_lshl_b32 s2, s31, 5
	v_and_b32_e32 v202, 31, v132
	s_or_b32 s0, s0, s2
	v_or_b32_e32 v176, s0, v202
	v_mad_u64_u32 v[16:17], s[0:1], v176, s20, v[172:173]
	s_lshl_b32 s0, s4, 7
	s_ashr_i32 s30, s34, 8
	s_and_b32 s0, s0, 0x180
	v_mad_i32_i24 v17, s3, v189, v17
	s_lshl_b32 s12, s0, 1
	s_lshl_b32 s0, s30, 6
	v_bfe_u32 v133, v132, 5, 1
	v_lshl_add_u64 v[16:17], v[16:17], 0, s[12:13]
	s_ashr_i32 s1, s0, 31
	v_lshl_add_u64 v[16:17], s[0:1], 1, v[16:17]
	v_lshlrev_b32_e32 v166, 4, v133
	v_lshl_add_u64 v[16:17], v[16:17], 0, v[166:167]
	global_load_dwordx4 v[90:93], v[16:17], off offset:3136
	global_load_dwordx4 v[96:99], v[16:17], off offset:3168
	global_load_dwordx4 v[108:111], v[16:17], off offset:3072
	global_load_dwordx4 v[112:115], v[16:17], off offset:3104
	v_cmp_lt_i32_e32 vcc, v191, v192
	s_or_b32 s0, s2, s5
	s_lshl_b32 s0, s0, 1
	v_cndmask_b32_e32 v16, v190, v191, vcc
	v_lshlrev_b32_e32 v195, 2, v16
	v_and_b32_e32 v16, 32, v132
	global_load_dwordx4 v[40:43], v16, s[62:63] offset:144
	global_load_dwordx4 v[44:47], v16, s[62:63] offset:128
	global_load_dwordx4 v[28:31], v16, s[62:63] offset:208
	global_load_dwordx4 v[36:39], v16, s[62:63] offset:192
	global_load_dwordx4 v[72:75], v16, s[62:63] offset:16
	global_load_dwordx4 v[76:79], v16, s[62:63]
	global_load_dwordx4 v[64:67], v16, s[62:63] offset:80
	global_load_dwordx4 v[68:71], v16, s[62:63] offset:64
	v_lshlrev_b32_e32 v48, 6, v133
	v_and_or_b32 v16, s2, 32, v202
	s_and_b32 s0, s0, 0x3f80
	v_lshl_or_b32 v32, v16, 7, v48
	v_or_b32_e32 v60, s0, v48
	global_load_dwordx4 v[16:19], v32, s[10:11] offset:48
	global_load_dwordx4 v[20:23], v32, s[10:11] offset:32
	global_load_dwordx4 v[24:27], v32, s[10:11] offset:16
	s_nop 0
	global_load_dwordx4 v[32:35], v32, s[10:11]
	s_nop 0
	global_load_dwordx4 v[48:51], v60, s[10:11] offset:48
	global_load_dwordx4 v[52:55], v60, s[10:11] offset:32
	global_load_dwordx4 v[56:59], v60, s[10:11] offset:16
	s_nop 0
	global_load_dwordx4 v[60:63], v60, s[10:11]
	v_mov_b32_e32 v177, s3
	v_cmp_gt_i32_e32 vcc, s21, v132
	s_waitcnt vmcnt(19)
	v_lshlrev_b32_e32 v84, 16, v93
	s_waitcnt vmcnt(18)
	v_lshlrev_b32_e32 v80, 16, v99
	v_and_b32_e32 v81, 0xffff0000, v99
	v_lshlrev_b32_e32 v82, 16, v98
	v_and_b32_e32 v83, 0xffff0000, v98
	s_waitcnt vmcnt(17)
	v_lshlrev_b32_e32 v98, 16, v111
	v_and_b32_e32 v99, 0xffff0000, v111
	v_lshlrev_b32_e32 v102, 16, v110
	v_and_b32_e32 v103, 0xffff0000, v110
	v_lshlrev_b32_e32 v110, 16, v108
	v_and_b32_e32 v111, 0xffff0000, v108
	v_lshlrev_b32_e32 v106, 16, v109
	v_and_b32_e32 v107, 0xffff0000, v109
	v_pk_mul_f32 v[148:149], v[110:111], v[110:111]
	v_pk_mul_f32 v[144:145], v[106:107], v[106:107]
	v_add_f32_e32 v148, v148, v149
	v_add_f32_e32 v144, v144, v148
	v_pk_mul_f32 v[142:143], v[102:103], v[102:103]
	v_add_f32_e32 v144, v145, v144
	v_add_f32_e32 v142, v142, v144
	v_pk_mul_f32 v[138:139], v[98:99], v[98:99]
	v_add_f32_e32 v142, v143, v142
	s_waitcnt vmcnt(16)
	v_lshlrev_b32_e32 v108, 16, v112
	v_and_b32_e32 v109, 0xffff0000, v112
	v_add_f32_e32 v138, v138, v142
	v_lshlrev_b32_e32 v104, 16, v113
	v_and_b32_e32 v105, 0xffff0000, v113
	v_pk_mul_f32 v[112:113], v[108:109], v[108:109]
	v_add_f32_e32 v138, v139, v138
	v_add_f32_e32 v112, v112, v138
	v_pk_mul_f32 v[146:147], v[104:105], v[104:105]
	v_add_f32_e32 v112, v113, v112
	v_lshlrev_b32_e32 v100, 16, v114
	v_and_b32_e32 v101, 0xffff0000, v114
	v_add_f32_e32 v112, v146, v112
	v_and_b32_e32 v85, 0xffff0000, v93
	v_lshlrev_b32_e32 v88, 16, v92
	v_and_b32_e32 v89, 0xffff0000, v92
	v_lshlrev_b32_e32 v92, 16, v91
	v_and_b32_e32 v93, 0xffff0000, v91
	v_lshlrev_b32_e32 v86, 16, v97
	v_and_b32_e32 v87, 0xffff0000, v97
	v_lshlrev_b32_e32 v94, 16, v90
	v_and_b32_e32 v95, 0xffff0000, v90
	v_lshlrev_b32_e32 v90, 16, v96
	v_and_b32_e32 v91, 0xffff0000, v96
	v_lshlrev_b32_e32 v96, 16, v115
	v_and_b32_e32 v97, 0xffff0000, v115
	v_pk_mul_f32 v[114:115], v[100:101], v[100:101]
	v_add_f32_e32 v112, v147, v112
	v_add_f32_e32 v112, v114, v112
	v_pk_mul_f32 v[140:141], v[96:97], v[96:97]
	v_add_f32_e32 v112, v115, v112
	v_add_f32_e32 v112, v140, v112
	v_pk_mul_f32 v[134:135], v[94:95], v[94:95]
	v_add_f32_e32 v112, v141, v112
	v_add_f32_e32 v112, v134, v112
	v_pk_mul_f32 v[124:125], v[92:93], v[92:93]
	v_add_f32_e32 v112, v135, v112
	v_add_f32_e32 v112, v124, v112
	v_pk_mul_f32 v[120:121], v[88:89], v[88:89]
	v_add_f32_e32 v112, v125, v112
	v_add_f32_e32 v112, v120, v112
	v_pk_mul_f32 v[116:117], v[84:85], v[84:85]
	v_add_f32_e32 v112, v121, v112
	v_add_f32_e32 v112, v116, v112
	v_pk_mul_f32 v[136:137], v[90:91], v[90:91]
	v_add_f32_e32 v112, v117, v112
	v_add_f32_e32 v112, v136, v112
	v_pk_mul_f32 v[126:127], v[86:87], v[86:87]
	v_add_f32_e32 v112, v137, v112
	v_add_f32_e32 v112, v126, v112
	v_pk_mul_f32 v[122:123], v[82:83], v[82:83]
	v_add_f32_e32 v112, v127, v112
	v_add_f32_e32 v112, v122, v112
	v_pk_mul_f32 v[118:119], v[80:81], v[80:81]
	v_add_f32_e32 v112, v123, v112
	v_add_f32_e32 v112, v118, v112
	v_add_f32_e32 v134, v119, v112
	ds_bpermute_b32 v135, v195, v134
	v_lshrrev_b32_e32 v112, 6, v188
	v_lshrrev_b32_e32 v113, 4, v190
	v_and_b32_e32 v114, 15, v190
	v_lshl_add_u32 v115, v112, 3, v113
	v_and_b32_e32 v116, 15, v115
	v_xor_b32_e32 v116, v114, v116
	v_mul_u32_u24_e32 v117, 0x1a00, v115
	v_lshl_add_u32 v181, v116, 4, v117
	v_add_u32_e32 v118, 4, v115
	v_and_b32_e32 v116, 15, v118
	v_xor_b32_e32 v116, v114, v116
	v_mul_u32_u24_e32 v118, 0x1a00, v118
	v_lshl_add_u32 v165, v116, 4, v118
	v_lshlrev_b32_e32 v116, 2, v113
	v_xor_b32_e32 v116, v114, v116
	v_lshl_add_u32 v116, v116, 4, v117
	v_add_u32_e32 v207, 0x400, v116
	v_add_u32_e32 v208, 0x6c00, v116
	s_lshl_b32 s1, s16, 8
	s_add_i32 s1, s1, 0x8000
	s_mul_i32 s2, s1, 0x1a00
	s_add_u32 s22, s8, s12
	s_addc_u32 s23, s9, 0
	s_add_u32 s22, s22, 0x1000
	s_addc_u32 s23, s23, 0
	s_add_u32 s36, s22, s2
	s_addc_u32 s37, s23, 0
	s_lshl_b32 s3, s16, 13
	s_mul_i32 s3, s3, 0x1a00
	s_add_u32 s38, s22, s3
	s_addc_u32 s39, s23, 0
	s_lshr_b32 s17, s34, 6
	s_lshl_b32 s17, s17, 11
	s_add_i32 m0, s17, 0
	s_nop 0
	global_load_lds_dwordx4 v181, s[36:37]
	s_add_i32 m0, s17, 1024
	s_nop 0
	global_load_lds_dwordx4 v165, s[36:37]
	s_add_i32 m0, s17, 16384
	s_nop 0
	global_load_lds_dwordx4 v207, s[36:37]
	s_add_i32 m0, s17, 17408
	s_nop 0
	global_load_lds_dwordx4 v208, s[36:37]
	s_add_u32 s36, s36, 0x68000
	s_addc_u32 s37, s37, 0
	s_add_i32 m0, s17, 32768
	s_nop 0
	global_load_lds_dwordx4 v181, s[36:37]
	s_add_i32 m0, s17, 33792
	s_nop 0
	global_load_lds_dwordx4 v165, s[36:37]
	s_add_i32 m0, s17, 49152
	s_nop 0
	global_load_lds_dwordx4 v207, s[36:37]
	s_add_i32 m0, s17, 50176
	s_nop 0
	global_load_lds_dwordx4 v208, s[36:37]
	s_add_u32 s36, s36, 0x68000
	s_addc_u32 s37, s37, 0
	s_add_i32 m0, s17, 65536
	s_nop 0
	global_load_lds_dwordx4 v181, s[36:37]
	s_add_i32 m0, s17, 66560
	s_nop 0
	global_load_lds_dwordx4 v165, s[36:37]
	s_add_i32 m0, s17, 81920
	s_nop 0
	global_load_lds_dwordx4 v207, s[36:37]
	s_add_i32 m0, s17, 82944
	s_nop 0
	global_load_lds_dwordx4 v208, s[36:37]
	s_add_u32 s36, s36, 0x68000
	s_addc_u32 s37, s37, 0
	v_and_b32_e32 v112, 31, v190
	v_lshrrev_b32_e32 v113, 5, v190
	v_lshrrev_b32_e32 v114, 8, v188
	v_lshl_or_b32 v113, v114, 3, v113
	v_and_b32_e32 v115, 15, v112
	v_xor_b32_e32 v113, v113, v115
	v_lshlrev_b32_e32 v112, 8, v112
	v_lshl_add_u32 v178, v113, 4, v112
	v_xor_b32_e32 v116, 2, v113
	v_lshl_add_u32 v128, v116, 4, v112
	v_xor_b32_e32 v116, 4, v113
	v_lshl_add_u32 v130, v116, 4, v112
	v_xor_b32_e32 v116, 6, v113
	v_lshl_add_u32 v131, v116, 4, v112
	v_add_u32_e32 v180, 0x10000, v178
	v_add_u32_e32 v189, 0x10000, v128
	v_add_u32_e32 v191, 0x10000, v130
	v_add_u32_e32 v192, 0x10000, v131
	v_and_b32_e32 v112, 3, v190
	v_bfe_u32 v113, v190, 2, 2
	v_bfe_u32 v114, v190, 4, 1
	v_lshrrev_b32_e32 v115, 5, v190
	v_lshlrev_b32_e32 v115, 10, v115
	v_lshl_add_u32 v115, v113, 8, v115
	v_lshl_add_u32 v115, v114, 5, v115
	v_lshl_add_u32 v115, v112, 3, v115
	v_add_u32_e32 v115, 0x4000, v115
	v_lshl_add_u32 v184, v113, 6, v115
	v_xor_b32_e32 v116, 1, v113
	v_lshl_add_u32 v185, v116, 6, v115
	v_xor_b32_e32 v116, 2, v113
	v_lshl_add_u32 v186, v116, 6, v115
	v_xor_b32_e32 v116, 3, v113
	v_lshl_add_u32 v187, v116, 6, v115
	v_add_u32_e32 v198, 0x10000, v184
	v_add_u32_e32 v199, 0x10000, v185
	v_add_u32_e32 v201, 0x10000, v186
	v_add_u32_e32 v203, 0x10000, v187
	v_mov_b32_e32 v148, 0
	v_mov_b32_e32 v149, 0
	v_mov_b32_e32 v150, 0
	v_mov_b32_e32 v151, 0
	v_lshlrev_b32_e32 v112, 4, v188
	v_add_u32_e32 v112, 0x1e000, v112
	ds_write_b128 v112, v[148:151]
	s_waitcnt vmcnt(12)
	s_waitcnt lgkmcnt(0)
	v_lshrrev_b32_e32 v136, 2, v132
	v_lshlrev_b32_e32 v179, 2, v133
	v_and_or_b32 v133, v136, 3, v179
	v_mul_u32_u24_e32 v204, 0x140, v133
	v_lshlrev_b32_e32 v133, 1, v132
	v_and_b32_e32 v205, 32, v133
	v_add_f32_e32 v133, v134, v135
	v_fmamk_f32 v133, v133, 0x3c800000, v193
	v_mul_f32_e32 v134, 0x4b800000, v133
	v_cmp_gt_f32_e32 vcc, s27, v133
	v_lshlrev_b32_e32 v132, 3, v132
	v_and_b32_e32 v206, 24, v132
	v_cndmask_b32_e32 v133, v133, v134, vcc
	v_rsq_f32_e32 v133, v133
	v_add3_u32 v197, v204, v205, v206
	v_add_u32_e32 v200, 0, v197
	s_lshl_b32 s0, s30, 7
	v_mul_f32_e32 v132, 0x45800000, v133
	v_cndmask_b32_e32 v132, v133, v132, vcc
	v_mul_f32_e32 v132, 0x3e38aa3b, v132
	v_pk_mul_f32 v[68:69], v[68:69], v[132:133] op_sel_hi:[1,0]
	v_pk_mul_f32 v[30:31], v[30:31], v[132:133] op_sel_hi:[1,0]
	v_pk_mul_f32 v[76:77], v[76:77], v[132:133] op_sel_hi:[1,0]
	v_pk_mul_f32 v[68:69], v[68:69], v[108:109]
	v_pk_mul_f32 v[30:31], v[30:31], v[80:81]
	v_mov_b32_e32 v80, v60
	v_mov_b32_e32 v81, v62
	v_mov_b32_e32 v62, v61
	v_pk_mul_f32 v[76:77], v[76:77], v[110:111]
	v_pk_mul_f32 v[70:71], v[70:71], v[132:133] op_sel_hi:[1,0]
	v_pk_mul_f32 v[60:61], v[62:63], v[68:69]
	v_pk_mul_f32 v[68:69], v[80:81], v[68:69]
	v_pk_mul_f32 v[78:79], v[78:79], v[132:133] op_sel_hi:[1,0]
	v_pk_mul_f32 v[70:71], v[70:71], v[104:105]
	v_pk_fma_f32 v[62:63], v[62:63], v[76:77], v[68:69]
	v_mov_b32_e32 v69, v58
	v_mov_b32_e32 v58, v57
	v_pk_mul_f32 v[78:79], v[78:79], v[106:107]
	v_mov_b32_e32 v68, v56
	v_pk_mul_f32 v[56:57], v[58:59], v[70:71]
	v_pk_mul_f32 v[64:65], v[64:65], v[132:133] op_sel_hi:[1,0]
	v_pk_fma_f32 v[56:57], v[68:69], v[78:79], v[56:57] neg_lo:[0,0,1] neg_hi:[0,0,1]
	v_pk_mul_f32 v[68:69], v[68:69], v[70:71]
	v_pk_mul_f32 v[72:73], v[72:73], v[132:133] op_sel_hi:[1,0]
	v_pk_mul_f32 v[64:65], v[64:65], v[100:101]
	v_pk_fma_f32 v[58:59], v[58:59], v[78:79], v[68:69]
	v_mov_b32_e32 v68, v52
	v_mov_b32_e32 v69, v54
	v_mov_b32_e32 v54, v53
	v_pk_mul_f32 v[72:73], v[72:73], v[102:103]
	v_pk_mul_f32 v[66:67], v[66:67], v[132:133] op_sel_hi:[1,0]
	v_pk_mul_f32 v[52:53], v[54:55], v[64:65]
	v_pk_mul_f32 v[64:65], v[68:69], v[64:65]
	v_pk_mul_f32 v[74:75], v[74:75], v[132:133] op_sel_hi:[1,0]
	v_pk_mul_f32 v[66:67], v[66:67], v[96:97]
	v_pk_fma_f32 v[54:55], v[54:55], v[72:73], v[64:65]
	v_mov_b32_e32 v65, v50
	v_mov_b32_e32 v50, v49
	v_pk_mul_f32 v[74:75], v[74:75], v[98:99]
	v_mov_b32_e32 v64, v48
	v_pk_mul_f32 v[48:49], v[50:51], v[66:67]
	v_pk_mul_f32 v[36:37], v[36:37], v[132:133] op_sel_hi:[1,0]
	v_pk_fma_f32 v[48:49], v[74:75], v[64:65], v[48:49] neg_lo:[0,0,1] neg_hi:[0,0,1]
	v_pk_mul_f32 v[64:65], v[64:65], v[66:67]
	v_pk_mul_f32 v[44:45], v[44:45], v[132:133] op_sel_hi:[1,0]
	v_pk_mul_f32 v[36:37], v[36:37], v[90:91]
	v_pk_fma_f32 v[50:51], v[50:51], v[74:75], v[64:65]
	v_mov_b32_e32 v64, v32
	v_mov_b32_e32 v65, v34
	v_mov_b32_e32 v34, v33
	v_pk_mul_f32 v[44:45], v[44:45], v[94:95]
	v_pk_mul_f32 v[38:39], v[38:39], v[132:133] op_sel_hi:[1,0]
	v_pk_mul_f32 v[32:33], v[36:37], v[34:35]
	v_pk_mul_f32 v[36:37], v[36:37], v[64:65]
	v_pk_mul_f32 v[46:47], v[46:47], v[132:133] op_sel_hi:[1,0]
	v_pk_mul_f32 v[38:39], v[38:39], v[86:87]
	v_pk_fma_f32 v[34:35], v[44:45], v[34:35], v[36:37]
	v_mov_b32_e32 v37, v26
	v_mov_b32_e32 v26, v25
	v_pk_mul_f32 v[46:47], v[46:47], v[92:93]
	v_mov_b32_e32 v36, v24
	v_pk_mul_f32 v[24:25], v[38:39], v[26:27]
	v_pk_mul_f32 v[28:29], v[28:29], v[132:133] op_sel_hi:[1,0]
	v_pk_fma_f32 v[24:25], v[46:47], v[36:37], v[24:25] neg_lo:[0,0,1] neg_hi:[0,0,1]
	v_pk_mul_f32 v[36:37], v[38:39], v[36:37]
	v_pk_mul_f32 v[40:41], v[40:41], v[132:133] op_sel_hi:[1,0]
	v_pk_mul_f32 v[28:29], v[28:29], v[82:83]
	v_pk_fma_f32 v[26:27], v[46:47], v[26:27], v[36:37]
	v_mov_b32_e32 v36, v20
	v_mov_b32_e32 v37, v22
	v_mov_b32_e32 v22, v21
	v_pk_mul_f32 v[40:41], v[40:41], v[88:89]
	v_pk_mul_f32 v[20:21], v[28:29], v[22:23]
	v_pk_mul_f32 v[28:29], v[28:29], v[36:37]
	v_pk_mul_f32 v[42:43], v[42:43], v[132:133] op_sel_hi:[1,0]
	v_pk_fma_f32 v[22:23], v[40:41], v[22:23], v[28:29]
	v_mov_b32_e32 v29, v18
	v_mov_b32_e32 v18, v17
	v_pk_mul_f32 v[42:43], v[42:43], v[84:85]
	v_mov_b32_e32 v28, v16
	v_pk_mul_f32 v[16:17], v[30:31], v[18:19]
	v_pk_fma_f32 v[60:61], v[80:81], v[76:77], v[60:61] neg_lo:[0,0,1] neg_hi:[0,0,1]
	v_pk_fma_f32 v[16:17], v[42:43], v[28:29], v[16:17] neg_lo:[0,0,1] neg_hi:[0,0,1]
	v_pk_mul_f32 v[28:29], v[30:31], v[28:29]
	v_pk_fma_f32 v[52:53], v[68:69], v[72:73], v[52:53] neg_lo:[0,0,1] neg_hi:[0,0,1]
	v_pk_fma_f32 v[32:33], v[44:45], v[64:65], v[32:33] neg_lo:[0,0,1] neg_hi:[0,0,1]
	v_pk_fma_f32 v[20:21], v[40:41], v[36:37], v[20:21] neg_lo:[0,0,1] neg_hi:[0,0,1]
	v_pk_fma_f32 v[18:19], v[42:43], v[18:19], v[28:29]
	v_cvt_pk_bf16_f32 v140, v60, v61
	v_cvt_pk_bf16_f32 v141, v56, v57
	v_cvt_pk_bf16_f32 v142, v52, v53
	v_cvt_pk_bf16_f32 v143, v48, v49
	v_cvt_pk_bf16_f32 v144, v62, v63
	v_cvt_pk_bf16_f32 v145, v58, v59
	v_cvt_pk_bf16_f32 v146, v54, v55
	v_cvt_pk_bf16_f32 v147, v50, v51
	v_cvt_pk_bf16_f32 v136, v32, v33
	v_cvt_pk_bf16_f32 v137, v24, v25
	v_cvt_pk_bf16_f32 v138, v20, v21
	v_cvt_pk_bf16_f32 v139, v16, v17
	v_cvt_pk_bf16_f32 v132, v34, v35
	v_cvt_pk_bf16_f32 v133, v26, v27
	v_cvt_pk_bf16_f32 v134, v22, v23
	v_cvt_pk_bf16_f32 v135, v18, v19
	v_mov_b32_e32 v64, 0
	v_mov_b32_e32 v65, 0
	v_mov_b32_e32 v66, 0
	v_mov_b32_e32 v67, 0
	v_mov_b32_e32 v68, 0
	v_mov_b32_e32 v69, 0
	v_mov_b32_e32 v70, 0
	v_mov_b32_e32 v71, 0
	v_mov_b32_e32 v72, 0
	v_mov_b32_e32 v73, 0
	v_mov_b32_e32 v74, 0
	v_mov_b32_e32 v75, 0
	v_mov_b32_e32 v76, 0
	v_mov_b32_e32 v77, 0
	v_mov_b32_e32 v78, 0
	v_mov_b32_e32 v79, 0
	v_mov_b32_e32 v48, 0
	v_mov_b32_e32 v49, 0
	v_mov_b32_e32 v50, 0
	v_mov_b32_e32 v51, 0
	v_mov_b32_e32 v52, 0
	v_mov_b32_e32 v53, 0
	v_mov_b32_e32 v54, 0
	v_mov_b32_e32 v55, 0
	v_mov_b32_e32 v56, 0
	v_mov_b32_e32 v57, 0
	v_mov_b32_e32 v58, 0
	v_mov_b32_e32 v59, 0
	v_mov_b32_e32 v60, 0
	v_mov_b32_e32 v61, 0
	v_mov_b32_e32 v62, 0
	v_mov_b32_e32 v63, 0
	v_mov_b32_e32 v32, 0
	v_mov_b32_e32 v33, 0
	v_mov_b32_e32 v34, 0
	v_mov_b32_e32 v35, 0
	v_mov_b32_e32 v36, 0
	v_mov_b32_e32 v37, 0
	v_mov_b32_e32 v38, 0
	v_mov_b32_e32 v39, 0
	v_mov_b32_e32 v40, 0
	v_mov_b32_e32 v41, 0
	v_mov_b32_e32 v42, 0
	v_mov_b32_e32 v43, 0
	v_mov_b32_e32 v44, 0
	v_mov_b32_e32 v45, 0
	v_mov_b32_e32 v46, 0
	v_mov_b32_e32 v47, 0
	v_mov_b32_e32 v16, 0
	v_mov_b32_e32 v17, 0
	v_mov_b32_e32 v18, 0
	v_mov_b32_e32 v19, 0
	v_mov_b32_e32 v20, 0
	v_mov_b32_e32 v21, 0
	v_mov_b32_e32 v22, 0
	v_mov_b32_e32 v23, 0
	v_mov_b32_e32 v24, 0
	v_mov_b32_e32 v25, 0
	v_mov_b32_e32 v26, 0
	v_mov_b32_e32 v27, 0
	v_mov_b32_e32 v28, 0
	v_mov_b32_e32 v29, 0
	v_mov_b32_e32 v30, 0
	v_mov_b32_e32 v31, 0
	v_mov_b32_e32 v80, 0xf149f2ca
	v_mov_b32_e32 v81, 0xf149f2ca
	v_mov_b32_e32 v82, 0xf149f2ca
	v_mov_b32_e32 v83, 0xf149f2ca
	v_mov_b32_e32 v84, 0xf149f2ca
	v_mov_b32_e32 v85, 0xf149f2ca
	v_mov_b32_e32 v86, 0xf149f2ca
	v_mov_b32_e32 v87, 0xf149f2ca
	v_mov_b32_e32 v88, 0xf149f2ca
	v_mov_b32_e32 v89, 0xf149f2ca
	v_mov_b32_e32 v90, 0xf149f2ca
	v_mov_b32_e32 v91, 0xf149f2ca
	v_mov_b32_e32 v92, 0xf149f2ca
	v_mov_b32_e32 v93, 0xf149f2ca
	v_mov_b32_e32 v94, 0xf149f2ca
	v_mov_b32_e32 v95, 0xf149f2ca
	v_mov_b32_e32 v225, 0
	v_mov_b32_e32 v166, 0
	v_mov_b32_e32 v175, 0
	v_mov_b32_e32 v202, 0
	s_waitcnt vmcnt(8)
	s_barrier
	ds_read_b128 v[112:115], v178
	ds_read_b128 v[116:119], v128
	ds_read_b128 v[120:123], v130
	ds_read_b128 v[124:127], v131
	s_mov_b32 s16, 0
.Latt_loop:
	s_waitcnt lgkmcnt(3)
	v_mfma_f32_32x32x16_bf16 v[96:111], v[112:115], v[140:143], v[0:15]
	v_exp_f32_e32 v209, v80
	v_exp_f32_e32 v210, v81
	ds_read_b64_tr_b16 v[226:227], v198 offset:40960
	ds_read_b64_tr_b16 v[228:229], v198 offset:43008
	s_waitcnt lgkmcnt(4)
	v_mfma_f32_32x32x16_bf16 v[96:111], v[116:119], v[144:147], v[96:111]
	v_exp_f32_e32 v211, v82
	v_exp_f32_e32 v212, v83
	v_cvt_pk_bf16_f32 v156, v209, v210
	ds_read_b64_tr_b16 v[230:231], v199 offset:40960
	ds_read_b64_tr_b16 v[232:233], v199 offset:43008
	s_waitcnt lgkmcnt(5)
	v_mfma_f32_32x32x16_bf16 v[96:111], v[120:123], v[136:139], v[96:111]
	v_exp_f32_e32 v213, v84
	v_exp_f32_e32 v214, v85
	v_cvt_pk_bf16_f32 v157, v211, v212
	ds_read_b64_tr_b16 v[234:235], v201 offset:40960
	ds_read_b64_tr_b16 v[236:237], v201 offset:43008
	s_waitcnt lgkmcnt(6)
	v_mfma_f32_32x32x16_bf16 v[96:111], v[124:127], v[132:135], v[96:111]
	v_exp_f32_e32 v215, v86
	v_exp_f32_e32 v216, v87
	v_cvt_pk_bf16_f32 v158, v213, v214
	v_cvt_pk_bf16_f32 v159, v215, v216
	ds_read_b64_tr_b16 v[238:239], v203 offset:40960
	ds_read_b64_tr_b16 v[240:241], v203 offset:43008
	s_waitcnt lgkmcnt(6)
	v_mfma_f32_32x32x16_bf16 v[64:79], v[226:229], v[156:159], v[64:79]
	v_exp_f32_e32 v217, v88
	v_exp_f32_e32 v218, v89
	ds_read_b64_tr_b16 v[242:243], v198 offset:45056
	ds_read_b64_tr_b16 v[244:245], v198 offset:47104
	s_waitcnt lgkmcnt(6)
	v_mfma_f32_32x32x16_bf16 v[48:63], v[230:233], v[156:159], v[48:63]
	v_exp_f32_e32 v219, v90
	v_exp_f32_e32 v220, v91
	v_cvt_pk_bf16_f32 v160, v217, v218
	ds_read_b64_tr_b16 v[246:247], v199 offset:45056
	ds_read_b64_tr_b16 v[248:249], v199 offset:47104
	s_waitcnt lgkmcnt(6)
	v_mfma_f32_32x32x16_bf16 v[32:47], v[234:237], v[156:159], v[32:47]
	v_exp_f32_e32 v221, v92
	v_exp_f32_e32 v222, v93
	v_cvt_pk_bf16_f32 v161, v219, v220
	ds_read_b64_tr_b16 v[226:227], v201 offset:45056
	ds_read_b64_tr_b16 v[228:229], v201 offset:47104
	s_waitcnt lgkmcnt(6)
	v_mfma_f32_32x32x16_bf16 v[16:31], v[238:241], v[156:159], v[16:31]
	v_exp_f32_e32 v223, v94
	v_exp_f32_e32 v224, v95
	v_cvt_pk_bf16_f32 v162, v221, v222
	v_cvt_pk_bf16_f32 v163, v223, v224
	ds_read_b64_tr_b16 v[230:231], v203 offset:45056
	ds_read_b64_tr_b16 v[232:233], v203 offset:47104
	s_waitcnt lgkmcnt(6)
	v_mfma_f32_32x32x16_bf16 v[64:79], v[242:245], v[160:163], v[64:79]
	v_add_f32_e32 v225, v225, v209
	v_add_f32_e32 v166, v166, v210
	v_add_f32_e32 v175, v175, v211
	v_add_f32_e32 v202, v202, v212
	ds_read_b128 v[112:115], v178 offset:8192
	s_waitcnt lgkmcnt(5)
	v_mfma_f32_32x32x16_bf16 v[48:63], v[246:249], v[160:163], v[48:63]
	v_add_f32_e32 v225, v225, v213
	v_add_f32_e32 v166, v166, v214
	v_add_f32_e32 v175, v175, v215
	v_add_f32_e32 v202, v202, v216
	ds_read_b128 v[116:119], v128 offset:8192
	s_waitcnt lgkmcnt(4)
	v_mfma_f32_32x32x16_bf16 v[32:47], v[226:229], v[160:163], v[32:47]
	v_add_f32_e32 v225, v225, v217
	v_add_f32_e32 v166, v166, v218
	v_add_f32_e32 v175, v175, v219
	v_add_f32_e32 v202, v202, v220
	ds_read_b128 v[120:123], v130 offset:8192
	s_waitcnt lgkmcnt(3)
	v_mfma_f32_32x32x16_bf16 v[16:31], v[230:233], v[160:163], v[16:31]
	v_add_f32_e32 v225, v225, v221
	v_add_f32_e32 v166, v166, v222
	v_add_f32_e32 v175, v175, v223
	v_add_f32_e32 v202, v202, v224
	ds_read_b128 v[124:127], v131 offset:8192
	s_waitcnt lgkmcnt(3)
	v_mfma_f32_32x32x16_bf16 v[80:95], v[112:115], v[140:143], v[0:15]
	v_exp_f32_e32 v209, v96
	v_exp_f32_e32 v210, v97
	ds_read_b64_tr_b16 v[234:235], v184
	ds_read_b64_tr_b16 v[236:237], v184 offset:2048
	s_waitcnt lgkmcnt(4)
	v_mfma_f32_32x32x16_bf16 v[80:95], v[116:119], v[144:147], v[80:95]
	v_exp_f32_e32 v211, v98
	v_exp_f32_e32 v212, v99
	v_cvt_pk_bf16_f32 v148, v209, v210
	ds_read_b64_tr_b16 v[238:239], v185
	ds_read_b64_tr_b16 v[240:241], v185 offset:2048
	s_waitcnt lgkmcnt(5)
	v_mfma_f32_32x32x16_bf16 v[80:95], v[120:123], v[136:139], v[80:95]
	v_exp_f32_e32 v213, v100
	v_exp_f32_e32 v214, v101
	v_cvt_pk_bf16_f32 v149, v211, v212
	ds_read_b64_tr_b16 v[242:243], v186
	ds_read_b64_tr_b16 v[244:245], v186 offset:2048
	s_waitcnt lgkmcnt(6)
	v_mfma_f32_32x32x16_bf16 v[80:95], v[124:127], v[132:135], v[80:95]
	v_exp_f32_e32 v215, v102
	v_exp_f32_e32 v216, v103
	v_cvt_pk_bf16_f32 v150, v213, v214
	v_cvt_pk_bf16_f32 v151, v215, v216
	ds_read_b64_tr_b16 v[246:247], v187
	ds_read_b64_tr_b16 v[248:249], v187 offset:2048
	s_waitcnt lgkmcnt(6)
	v_mfma_f32_32x32x16_bf16 v[64:79], v[234:237], v[148:151], v[64:79]
	v_exp_f32_e32 v217, v104
	v_exp_f32_e32 v218, v105
	ds_read_b64_tr_b16 v[226:227], v184 offset:4096
	ds_read_b64_tr_b16 v[228:229], v184 offset:6144
	s_waitcnt lgkmcnt(6)
	v_mfma_f32_32x32x16_bf16 v[48:63], v[238:241], v[148:151], v[48:63]
	v_exp_f32_e32 v219, v106
	v_exp_f32_e32 v220, v107
	v_cvt_pk_bf16_f32 v152, v217, v218
	ds_read_b64_tr_b16 v[230:231], v185 offset:4096
	ds_read_b64_tr_b16 v[232:233], v185 offset:6144
	s_waitcnt lgkmcnt(6)
	v_mfma_f32_32x32x16_bf16 v[32:47], v[242:245], v[148:151], v[32:47]
	v_exp_f32_e32 v221, v108
	v_exp_f32_e32 v222, v109
	v_cvt_pk_bf16_f32 v153, v219, v220
	ds_read_b64_tr_b16 v[234:235], v186 offset:4096
	ds_read_b64_tr_b16 v[236:237], v186 offset:6144
	s_waitcnt lgkmcnt(6)
	v_mfma_f32_32x32x16_bf16 v[16:31], v[246:249], v[148:151], v[16:31]
	v_exp_f32_e32 v223, v110
	v_exp_f32_e32 v224, v111
	v_cvt_pk_bf16_f32 v154, v221, v222
	v_cvt_pk_bf16_f32 v155, v223, v224
	ds_read_b64_tr_b16 v[238:239], v187 offset:4096
	ds_read_b64_tr_b16 v[240:241], v187 offset:6144
	s_waitcnt lgkmcnt(6)
	v_mfma_f32_32x32x16_bf16 v[64:79], v[226:229], v[152:155], v[64:79]
	s_waitcnt vmcnt(4)
	s_barrier
	s_and_b32 s1, s35, 3
	s_add_i32 s35, s35, 1
	s_cmp_lg_u32 s1, 0
	s_cbranch_scc1 .Latt_bs_0
	v_lshlrev_b32_e32 v204, 16, v194
	v_and_b32_e32 v205, 0xffff0000, v194
	v_fma_f32 v182, v174, v182, v204
	v_fma_f32 v183, v174, v183, v205
	s_lshr_b32 s1, s35, 2
	s_add_i32 s1, s1, 1
	s_cmpk_lt_u32 s1, 0x84
	s_cbranch_scc0 .Latt_bs_0
	s_lshl_b32 s2, s1, 14
	s_mov_b32 s3, 0
	s_lshl_b32 s4, s1, 8
	s_mov_b32 s5, 0
	v_lshl_add_u64 v[204:205], v[168:169], 0, s[2:3]
	v_lshl_add_u64 v[196:197], v[170:171], 0, s[4:5]
	v_cvt_pk_bf16_f32 v206, v182, v183
	global_load_dword v194, v[204:205], off
	global_load_dword v174, v[196:197], off
	global_store_dword v[204:205], v206, off
.Latt_bs_0:
	v_add_f32_e32 v225, v225, v209
	v_add_f32_e32 v166, v166, v210
	v_add_f32_e32 v175, v175, v211
	v_add_f32_e32 v202, v202, v212
	s_add_i32 m0, s17, 98304
	ds_read_b128 v[112:115], v178 offset:32768
	global_load_lds_dwordx4 v181, s[36:37]
	s_waitcnt lgkmcnt(5)
	v_mfma_f32_32x32x16_bf16 v[48:63], v[230:233], v[152:155], v[48:63]
	v_add_f32_e32 v225, v225, v213
	v_add_f32_e32 v166, v166, v214
	v_add_f32_e32 v175, v175, v215
	v_add_f32_e32 v202, v202, v216
	s_add_i32 m0, s17, 99328
	ds_read_b128 v[116:119], v128 offset:32768
	global_load_lds_dwordx4 v165, s[36:37]
	s_waitcnt lgkmcnt(4)
	v_mfma_f32_32x32x16_bf16 v[32:47], v[234:237], v[152:155], v[32:47]
	v_add_f32_e32 v225, v225, v217
	v_add_f32_e32 v166, v166, v218
	v_add_f32_e32 v175, v175, v219
	v_add_f32_e32 v202, v202, v220
	s_add_i32 m0, s17, 114688
	ds_read_b128 v[120:123], v130 offset:32768
	global_load_lds_dwordx4 v207, s[36:37]
	s_waitcnt lgkmcnt(3)
	v_mfma_f32_32x32x16_bf16 v[16:31], v[238:241], v[152:155], v[16:31]
	v_add_f32_e32 v225, v225, v221
	v_add_f32_e32 v166, v166, v222
	v_add_f32_e32 v175, v175, v223
	v_add_f32_e32 v202, v202, v224
	s_add_i32 m0, s17, 115712
	ds_read_b128 v[124:127], v131 offset:32768
	global_load_lds_dwordx4 v208, s[36:37]
	s_add_u32 s36, s36, 0x68000
	s_addc_u32 s37, s37, 0
	s_cmp_eq_u32 s16, 0
	s_cselect_b32 s36, s38, s36
	s_cselect_b32 s37, s39, s37
	s_add_i32 s16, s16, 1
	s_waitcnt lgkmcnt(3)
	v_mfma_f32_32x32x16_bf16 v[96:111], v[112:115], v[140:143], v[0:15]
	v_exp_f32_e32 v209, v80
	v_exp_f32_e32 v210, v81
	ds_read_b64_tr_b16 v[242:243], v184 offset:8192
	ds_read_b64_tr_b16 v[244:245], v184 offset:10240
	s_waitcnt lgkmcnt(4)
	v_mfma_f32_32x32x16_bf16 v[96:111], v[116:119], v[144:147], v[96:111]
	v_exp_f32_e32 v211, v82
	v_exp_f32_e32 v212, v83
	v_cvt_pk_bf16_f32 v156, v209, v210
	ds_read_b64_tr_b16 v[246:247], v185 offset:8192
	ds_read_b64_tr_b16 v[248:249], v185 offset:10240
	s_waitcnt lgkmcnt(5)
	v_mfma_f32_32x32x16_bf16 v[96:111], v[120:123], v[136:139], v[96:111]
	v_exp_f32_e32 v213, v84
	v_exp_f32_e32 v214, v85
	v_cvt_pk_bf16_f32 v157, v211, v212
	ds_read_b64_tr_b16 v[226:227], v186 offset:8192
	ds_read_b64_tr_b16 v[228:229], v186 offset:10240
	s_waitcnt lgkmcnt(6)
	v_mfma_f32_32x32x16_bf16 v[96:111], v[124:127], v[132:135], v[96:111]
	v_exp_f32_e32 v215, v86
	v_exp_f32_e32 v216, v87
	v_cvt_pk_bf16_f32 v158, v213, v214
	v_cvt_pk_bf16_f32 v159, v215, v216
	ds_read_b64_tr_b16 v[230:231], v187 offset:8192
	ds_read_b64_tr_b16 v[232:233], v187 offset:10240
	s_waitcnt lgkmcnt(6)
	v_mfma_f32_32x32x16_bf16 v[64:79], v[242:245], v[156:159], v[64:79]
	v_exp_f32_e32 v217, v88
	v_exp_f32_e32 v218, v89
	ds_read_b64_tr_b16 v[234:235], v184 offset:12288
	ds_read_b64_tr_b16 v[236:237], v184 offset:14336
	s_waitcnt lgkmcnt(6)
	v_mfma_f32_32x32x16_bf16 v[48:63], v[246:249], v[156:159], v[48:63]
	v_exp_f32_e32 v219, v90
	v_exp_f32_e32 v220, v91
	v_cvt_pk_bf16_f32 v160, v217, v218
	ds_read_b64_tr_b16 v[238:239], v185 offset:12288
	ds_read_b64_tr_b16 v[240:241], v185 offset:14336
	s_waitcnt lgkmcnt(6)
	v_mfma_f32_32x32x16_bf16 v[32:47], v[226:229], v[156:159], v[32:47]
	v_exp_f32_e32 v221, v92
	v_exp_f32_e32 v222, v93
	v_cvt_pk_bf16_f32 v161, v219, v220
	ds_read_b64_tr_b16 v[242:243], v186 offset:12288
	ds_read_b64_tr_b16 v[244:245], v186 offset:14336
	s_waitcnt lgkmcnt(6)
	v_mfma_f32_32x32x16_bf16 v[16:31], v[230:233], v[156:159], v[16:31]
	v_exp_f32_e32 v223, v94
	v_exp_f32_e32 v224, v95
	v_cvt_pk_bf16_f32 v162, v221, v222
	v_cvt_pk_bf16_f32 v163, v223, v224
	ds_read_b64_tr_b16 v[246:247], v187 offset:12288
	ds_read_b64_tr_b16 v[248:249], v187 offset:14336
	s_waitcnt lgkmcnt(6)
	v_mfma_f32_32x32x16_bf16 v[64:79], v[234:237], v[160:163], v[64:79]
	v_add_f32_e32 v225, v225, v209
	v_add_f32_e32 v166, v166, v210
	v_add_f32_e32 v175, v175, v211
	v_add_f32_e32 v202, v202, v212
	ds_read_b128 v[112:115], v178 offset:40960
	s_waitcnt lgkmcnt(5)
	v_mfma_f32_32x32x16_bf16 v[48:63], v[238:241], v[160:163], v[48:63]
	v_add_f32_e32 v225, v225, v213
	v_add_f32_e32 v166, v166, v214
	v_add_f32_e32 v175, v175, v215
	v_add_f32_e32 v202, v202, v216
	ds_read_b128 v[116:119], v128 offset:40960
	s_waitcnt lgkmcnt(4)
	v_mfma_f32_32x32x16_bf16 v[32:47], v[242:245], v[160:163], v[32:47]
	v_add_f32_e32 v225, v225, v217
	v_add_f32_e32 v166, v166, v218
	v_add_f32_e32 v175, v175, v219
	v_add_f32_e32 v202, v202, v220
	ds_read_b128 v[120:123], v130 offset:40960
	s_waitcnt lgkmcnt(3)
	v_mfma_f32_32x32x16_bf16 v[16:31], v[246:249], v[160:163], v[16:31]
	v_add_f32_e32 v225, v225, v221
	v_add_f32_e32 v166, v166, v222
	v_add_f32_e32 v175, v175, v223
	v_add_f32_e32 v202, v202, v224
	ds_read_b128 v[124:127], v131 offset:40960
	s_waitcnt lgkmcnt(3)
	v_mfma_f32_32x32x16_bf16 v[80:95], v[112:115], v[140:143], v[0:15]
	v_exp_f32_e32 v209, v96
	v_exp_f32_e32 v210, v97
	ds_read_b64_tr_b16 v[226:227], v184 offset:32768
	ds_read_b64_tr_b16 v[228:229], v184 offset:34816
	s_waitcnt lgkmcnt(4)
	v_mfma_f32_32x32x16_bf16 v[80:95], v[116:119], v[144:147], v[80:95]
	v_exp_f32_e32 v211, v98
	v_exp_f32_e32 v212, v99
	v_cvt_pk_bf16_f32 v148, v209, v210
	ds_read_b64_tr_b16 v[230:231], v185 offset:32768
	ds_read_b64_tr_b16 v[232:233], v185 offset:34816
	s_waitcnt lgkmcnt(5)
	v_mfma_f32_32x32x16_bf16 v[80:95], v[120:123], v[136:139], v[80:95]
	v_exp_f32_e32 v213, v100
	v_exp_f32_e32 v214, v101
	v_cvt_pk_bf16_f32 v149, v211, v212
	ds_read_b64_tr_b16 v[234:235], v186 offset:32768
	ds_read_b64_tr_b16 v[236:237], v186 offset:34816
	s_waitcnt lgkmcnt(6)
	v_mfma_f32_32x32x16_bf16 v[80:95], v[124:127], v[132:135], v[80:95]
	v_exp_f32_e32 v215, v102
	v_exp_f32_e32 v216, v103
	v_cvt_pk_bf16_f32 v150, v213, v214
	v_cvt_pk_bf16_f32 v151, v215, v216
	ds_read_b64_tr_b16 v[238:239], v187 offset:32768
	ds_read_b64_tr_b16 v[240:241], v187 offset:34816
	s_waitcnt lgkmcnt(6)
	v_mfma_f32_32x32x16_bf16 v[64:79], v[226:229], v[148:151], v[64:79]
	v_exp_f32_e32 v217, v104
	v_exp_f32_e32 v218, v105
	ds_read_b64_tr_b16 v[242:243], v184 offset:36864
	ds_read_b64_tr_b16 v[244:245], v184 offset:38912
	s_waitcnt lgkmcnt(6)
	v_mfma_f32_32x32x16_bf16 v[48:63], v[230:233], v[148:151], v[48:63]
	v_exp_f32_e32 v219, v106
	v_exp_f32_e32 v220, v107
	v_cvt_pk_bf16_f32 v152, v217, v218
	ds_read_b64_tr_b16 v[246:247], v185 offset:36864
	ds_read_b64_tr_b16 v[248:249], v185 offset:38912
	s_waitcnt lgkmcnt(6)
	v_mfma_f32_32x32x16_bf16 v[32:47], v[234:237], v[148:151], v[32:47]
	v_exp_f32_e32 v221, v108
	v_exp_f32_e32 v222, v109
	v_cvt_pk_bf16_f32 v153, v219, v220
	ds_read_b64_tr_b16 v[226:227], v186 offset:36864
	ds_read_b64_tr_b16 v[228:229], v186 offset:38912
	s_waitcnt lgkmcnt(6)
	v_mfma_f32_32x32x16_bf16 v[16:31], v[238:241], v[148:151], v[16:31]
	v_exp_f32_e32 v223, v110
	v_exp_f32_e32 v224, v111
	v_cvt_pk_bf16_f32 v154, v221, v222
	v_cvt_pk_bf16_f32 v155, v223, v224
	ds_read_b64_tr_b16 v[230:231], v187 offset:36864
	ds_read_b64_tr_b16 v[232:233], v187 offset:38912
	s_waitcnt lgkmcnt(6)
	v_mfma_f32_32x32x16_bf16 v[64:79], v[242:245], v[152:155], v[64:79]
	s_waitcnt vmcnt(4)
	s_barrier
	s_and_b32 s1, s35, 3
	s_add_i32 s35, s35, 1
	s_cmp_lg_u32 s1, 0
	s_cbranch_scc1 .Latt_bs_1
	v_lshlrev_b32_e32 v204, 16, v194
	v_and_b32_e32 v205, 0xffff0000, v194
	v_fma_f32 v182, v174, v182, v204
	v_fma_f32 v183, v174, v183, v205
	s_lshr_b32 s1, s35, 2
	s_add_i32 s1, s1, 1
	s_cmpk_lt_u32 s1, 0x84
	s_cbranch_scc0 .Latt_bs_1
	s_lshl_b32 s2, s1, 14
	s_mov_b32 s3, 0
	s_lshl_b32 s4, s1, 8
	s_mov_b32 s5, 0
	v_lshl_add_u64 v[204:205], v[168:169], 0, s[2:3]
	v_lshl_add_u64 v[196:197], v[170:171], 0, s[4:5]
	v_cvt_pk_bf16_f32 v206, v182, v183
	global_load_dword v194, v[204:205], off
	global_load_dword v174, v[196:197], off
	global_store_dword v[204:205], v206, off
.Latt_bs_1:
	v_add_f32_e32 v225, v225, v209
	v_add_f32_e32 v166, v166, v210
	v_add_f32_e32 v175, v175, v211
	v_add_f32_e32 v202, v202, v212
	s_add_i32 m0, s17, 0
	ds_read_b128 v[112:115], v180
	global_load_lds_dwordx4 v181, s[36:37]
	s_waitcnt lgkmcnt(5)
	v_mfma_f32_32x32x16_bf16 v[48:63], v[246:249], v[152:155], v[48:63]
	v_add_f32_e32 v225, v225, v213
	v_add_f32_e32 v166, v166, v214
	v_add_f32_e32 v175, v175, v215
	v_add_f32_e32 v202, v202, v216
	s_add_i32 m0, s17, 1024
	ds_read_b128 v[116:119], v189
	global_load_lds_dwordx4 v165, s[36:37]
	s_waitcnt lgkmcnt(4)
	v_mfma_f32_32x32x16_bf16 v[32:47], v[226:229], v[152:155], v[32:47]
	v_add_f32_e32 v225, v225, v217
	v_add_f32_e32 v166, v166, v218
	v_add_f32_e32 v175, v175, v219
	v_add_f32_e32 v202, v202, v220
	s_add_i32 m0, s17, 16384
	ds_read_b128 v[120:123], v191
	global_load_lds_dwordx4 v207, s[36:37]
	s_waitcnt lgkmcnt(3)
	v_mfma_f32_32x32x16_bf16 v[16:31], v[230:233], v[152:155], v[16:31]
	v_add_f32_e32 v225, v225, v221
	v_add_f32_e32 v166, v166, v222
	v_add_f32_e32 v175, v175, v223
	v_add_f32_e32 v202, v202, v224
	s_add_i32 m0, s17, 17408
	ds_read_b128 v[124:127], v192
	global_load_lds_dwordx4 v208, s[36:37]
	s_add_u32 s36, s36, 0x68000
	s_addc_u32 s37, s37, 0
	s_cmp_eq_u32 s16, 0
	s_cselect_b32 s36, s38, s36
	s_cselect_b32 s37, s39, s37
	s_add_i32 s16, s16, 1
	s_waitcnt lgkmcnt(3)
	v_mfma_f32_32x32x16_bf16 v[96:111], v[112:115], v[140:143], v[0:15]
	v_exp_f32_e32 v209, v80
	v_exp_f32_e32 v210, v81
	ds_read_b64_tr_b16 v[234:235], v184 offset:40960
	ds_read_b64_tr_b16 v[236:237], v184 offset:43008
	s_waitcnt lgkmcnt(4)
	v_mfma_f32_32x32x16_bf16 v[96:111], v[116:119], v[144:147], v[96:111]
	v_exp_f32_e32 v211, v82
	v_exp_f32_e32 v212, v83
	v_cvt_pk_bf16_f32 v156, v209, v210
	ds_read_b64_tr_b16 v[238:239], v185 offset:40960
	ds_read_b64_tr_b16 v[240:241], v185 offset:43008
	s_waitcnt lgkmcnt(5)
	v_mfma_f32_32x32x16_bf16 v[96:111], v[120:123], v[136:139], v[96:111]
	v_exp_f32_e32 v213, v84
	v_exp_f32_e32 v214, v85
	v_cvt_pk_bf16_f32 v157, v211, v212
	ds_read_b64_tr_b16 v[242:243], v186 offset:40960
	ds_read_b64_tr_b16 v[244:245], v186 offset:43008
	s_waitcnt lgkmcnt(6)
	v_mfma_f32_32x32x16_bf16 v[96:111], v[124:127], v[132:135], v[96:111]
	v_exp_f32_e32 v215, v86
	v_exp_f32_e32 v216, v87
	v_cvt_pk_bf16_f32 v158, v213, v214
	v_cvt_pk_bf16_f32 v159, v215, v216
	ds_read_b64_tr_b16 v[246:247], v187 offset:40960
	ds_read_b64_tr_b16 v[248:249], v187 offset:43008
	s_waitcnt lgkmcnt(6)
	v_mfma_f32_32x32x16_bf16 v[64:79], v[234:237], v[156:159], v[64:79]
	v_exp_f32_e32 v217, v88
	v_exp_f32_e32 v218, v89
	ds_read_b64_tr_b16 v[226:227], v184 offset:45056
	ds_read_b64_tr_b16 v[228:229], v184 offset:47104
	s_waitcnt lgkmcnt(6)
	v_mfma_f32_32x32x16_bf16 v[48:63], v[238:241], v[156:159], v[48:63]
	v_exp_f32_e32 v219, v90
	v_exp_f32_e32 v220, v91
	v_cvt_pk_bf16_f32 v160, v217, v218
	ds_read_b64_tr_b16 v[230:231], v185 offset:45056
	ds_read_b64_tr_b16 v[232:233], v185 offset:47104
	s_waitcnt lgkmcnt(6)
	v_mfma_f32_32x32x16_bf16 v[32:47], v[242:245], v[156:159], v[32:47]
	v_exp_f32_e32 v221, v92
	v_exp_f32_e32 v222, v93
	v_cvt_pk_bf16_f32 v161, v219, v220
	ds_read_b64_tr_b16 v[234:235], v186 offset:45056
	ds_read_b64_tr_b16 v[236:237], v186 offset:47104
	s_waitcnt lgkmcnt(6)
	v_mfma_f32_32x32x16_bf16 v[16:31], v[246:249], v[156:159], v[16:31]
	v_exp_f32_e32 v223, v94
	v_exp_f32_e32 v224, v95
	v_cvt_pk_bf16_f32 v162, v221, v222
	v_cvt_pk_bf16_f32 v163, v223, v224
	ds_read_b64_tr_b16 v[238:239], v187 offset:45056
	ds_read_b64_tr_b16 v[240:241], v187 offset:47104
	s_waitcnt lgkmcnt(6)
	v_mfma_f32_32x32x16_bf16 v[64:79], v[226:229], v[160:163], v[64:79]
	v_add_f32_e32 v225, v225, v209
	v_add_f32_e32 v166, v166, v210
	v_add_f32_e32 v175, v175, v211
	v_add_f32_e32 v202, v202, v212
	ds_read_b128 v[112:115], v180 offset:8192
	s_waitcnt lgkmcnt(5)
	v_mfma_f32_32x32x16_bf16 v[48:63], v[230:233], v[160:163], v[48:63]
	v_add_f32_e32 v225, v225, v213
	v_add_f32_e32 v166, v166, v214
	v_add_f32_e32 v175, v175, v215
	v_add_f32_e32 v202, v202, v216
	ds_read_b128 v[116:119], v189 offset:8192
	s_waitcnt lgkmcnt(4)
	v_mfma_f32_32x32x16_bf16 v[32:47], v[234:237], v[160:163], v[32:47]
	v_add_f32_e32 v225, v225, v217
	v_add_f32_e32 v166, v166, v218
	v_add_f32_e32 v175, v175, v219
	v_add_f32_e32 v202, v202, v220
	ds_read_b128 v[120:123], v191 offset:8192
	s_waitcnt lgkmcnt(3)
	v_mfma_f32_32x32x16_bf16 v[16:31], v[238:241], v[160:163], v[16:31]
	v_add_f32_e32 v225, v225, v221
	v_add_f32_e32 v166, v166, v222
	v_add_f32_e32 v175, v175, v223
	v_add_f32_e32 v202, v202, v224
	ds_read_b128 v[124:127], v192 offset:8192
	s_waitcnt lgkmcnt(3)
	v_mfma_f32_32x32x16_bf16 v[80:95], v[112:115], v[140:143], v[0:15]
	v_exp_f32_e32 v209, v96
	v_exp_f32_e32 v210, v97
	ds_read_b64_tr_b16 v[242:243], v198
	ds_read_b64_tr_b16 v[244:245], v198 offset:2048
	s_waitcnt lgkmcnt(4)
	v_mfma_f32_32x32x16_bf16 v[80:95], v[116:119], v[144:147], v[80:95]
	v_exp_f32_e32 v211, v98
	v_exp_f32_e32 v212, v99
	v_cvt_pk_bf16_f32 v148, v209, v210
	ds_read_b64_tr_b16 v[246:247], v199
	ds_read_b64_tr_b16 v[248:249], v199 offset:2048
	s_waitcnt lgkmcnt(5)
	v_mfma_f32_32x32x16_bf16 v[80:95], v[120:123], v[136:139], v[80:95]
	v_exp_f32_e32 v213, v100
	v_exp_f32_e32 v214, v101
	v_cvt_pk_bf16_f32 v149, v211, v212
	ds_read_b64_tr_b16 v[226:227], v201
	ds_read_b64_tr_b16 v[228:229], v201 offset:2048
	s_waitcnt lgkmcnt(6)
	v_mfma_f32_32x32x16_bf16 v[80:95], v[124:127], v[132:135], v[80:95]
	v_exp_f32_e32 v215, v102
	v_exp_f32_e32 v216, v103
	v_cvt_pk_bf16_f32 v150, v213, v214
	v_cvt_pk_bf16_f32 v151, v215, v216
	ds_read_b64_tr_b16 v[230:231], v203
	ds_read_b64_tr_b16 v[232:233], v203 offset:2048
	s_waitcnt lgkmcnt(6)
	v_mfma_f32_32x32x16_bf16 v[64:79], v[242:245], v[148:151], v[64:79]
	v_exp_f32_e32 v217, v104
	v_exp_f32_e32 v218, v105
	ds_read_b64_tr_b16 v[234:235], v198 offset:4096
	ds_read_b64_tr_b16 v[236:237], v198 offset:6144
	s_waitcnt lgkmcnt(6)
	v_mfma_f32_32x32x16_bf16 v[48:63], v[246:249], v[148:151], v[48:63]
	v_exp_f32_e32 v219, v106
	v_exp_f32_e32 v220, v107
	v_cvt_pk_bf16_f32 v152, v217, v218
	ds_read_b64_tr_b16 v[238:239], v199 offset:4096
	ds_read_b64_tr_b16 v[240:241], v199 offset:6144
	s_waitcnt lgkmcnt(6)
	v_mfma_f32_32x32x16_bf16 v[32:47], v[226:229], v[148:151], v[32:47]
	v_exp_f32_e32 v221, v108
	v_exp_f32_e32 v222, v109
	v_cvt_pk_bf16_f32 v153, v219, v220
	ds_read_b64_tr_b16 v[242:243], v201 offset:4096
	ds_read_b64_tr_b16 v[244:245], v201 offset:6144
	s_waitcnt lgkmcnt(6)
	v_mfma_f32_32x32x16_bf16 v[16:31], v[230:233], v[148:151], v[16:31]
	v_exp_f32_e32 v223, v110
	v_exp_f32_e32 v224, v111
	v_cvt_pk_bf16_f32 v154, v221, v222
	v_cvt_pk_bf16_f32 v155, v223, v224
	ds_read_b64_tr_b16 v[246:247], v203 offset:4096
	ds_read_b64_tr_b16 v[248:249], v203 offset:6144
	s_waitcnt lgkmcnt(6)
	v_mfma_f32_32x32x16_bf16 v[64:79], v[234:237], v[152:155], v[64:79]
	s_waitcnt vmcnt(4)
	s_barrier
	s_and_b32 s1, s35, 3
	s_add_i32 s35, s35, 1
	s_cmp_lg_u32 s1, 0
	s_cbranch_scc1 .Latt_bs_2
	v_lshlrev_b32_e32 v204, 16, v194
	v_and_b32_e32 v205, 0xffff0000, v194
	v_fma_f32 v182, v174, v182, v204
	v_fma_f32 v183, v174, v183, v205
	s_lshr_b32 s1, s35, 2
	s_add_i32 s1, s1, 1
	s_cmpk_lt_u32 s1, 0x84
	s_cbranch_scc0 .Latt_bs_2
	s_lshl_b32 s2, s1, 14
	s_mov_b32 s3, 0
	s_lshl_b32 s4, s1, 8
	s_mov_b32 s5, 0
	v_lshl_add_u64 v[204:205], v[168:169], 0, s[2:3]
	v_lshl_add_u64 v[196:197], v[170:171], 0, s[4:5]
	v_cvt_pk_bf16_f32 v206, v182, v183
	global_load_dword v194, v[204:205], off
	global_load_dword v174, v[196:197], off
	global_store_dword v[204:205], v206, off
.Latt_bs_2:
	v_add_f32_e32 v225, v225, v209
	v_add_f32_e32 v166, v166, v210
	v_add_f32_e32 v175, v175, v211
	v_add_f32_e32 v202, v202, v212
	s_add_i32 m0, s17, 32768
	ds_read_b128 v[112:115], v180 offset:32768
	global_load_lds_dwordx4 v181, s[36:37]
	s_waitcnt lgkmcnt(5)
	v_mfma_f32_32x32x16_bf16 v[48:63], v[238:241], v[152:155], v[48:63]
	v_add_f32_e32 v225, v225, v213
	v_add_f32_e32 v166, v166, v214
	v_add_f32_e32 v175, v175, v215
	v_add_f32_e32 v202, v202, v216
	s_add_i32 m0, s17, 33792
	ds_read_b128 v[116:119], v189 offset:32768
	global_load_lds_dwordx4 v165, s[36:37]
	s_waitcnt lgkmcnt(4)
	v_mfma_f32_32x32x16_bf16 v[32:47], v[242:245], v[152:155], v[32:47]
	v_add_f32_e32 v225, v225, v217
	v_add_f32_e32 v166, v166, v218
	v_add_f32_e32 v175, v175, v219
	v_add_f32_e32 v202, v202, v220
	s_add_i32 m0, s17, 49152
	ds_read_b128 v[120:123], v191 offset:32768
	global_load_lds_dwordx4 v207, s[36:37]
	s_waitcnt lgkmcnt(3)
	v_mfma_f32_32x32x16_bf16 v[16:31], v[246:249], v[152:155], v[16:31]
	v_add_f32_e32 v225, v225, v221
	v_add_f32_e32 v166, v166, v222
	v_add_f32_e32 v175, v175, v223
	v_add_f32_e32 v202, v202, v224
	s_add_i32 m0, s17, 50176
	ds_read_b128 v[124:127], v192 offset:32768
	global_load_lds_dwordx4 v208, s[36:37]
	s_add_u32 s36, s36, 0x68000
	s_addc_u32 s37, s37, 0
	s_cmp_eq_u32 s16, 0
	s_cselect_b32 s36, s38, s36
	s_cselect_b32 s37, s39, s37
	s_add_i32 s16, s16, 1
	s_waitcnt lgkmcnt(3)
	v_mfma_f32_32x32x16_bf16 v[96:111], v[112:115], v[140:143], v[0:15]
	v_exp_f32_e32 v209, v80
	v_exp_f32_e32 v210, v81
	ds_read_b64_tr_b16 v[226:227], v198 offset:8192
	ds_read_b64_tr_b16 v[228:229], v198 offset:10240
	s_waitcnt lgkmcnt(4)
	v_mfma_f32_32x32x16_bf16 v[96:111], v[116:119], v[144:147], v[96:111]
	v_exp_f32_e32 v211, v82
	v_exp_f32_e32 v212, v83
	v_cvt_pk_bf16_f32 v156, v209, v210
	ds_read_b64_tr_b16 v[230:231], v199 offset:8192
	ds_read_b64_tr_b16 v[232:233], v199 offset:10240
	s_waitcnt lgkmcnt(5)
	v_mfma_f32_32x32x16_bf16 v[96:111], v[120:123], v[136:139], v[96:111]
	v_exp_f32_e32 v213, v84
	v_exp_f32_e32 v214, v85
	v_cvt_pk_bf16_f32 v157, v211, v212
	ds_read_b64_tr_b16 v[234:235], v201 offset:8192
	ds_read_b64_tr_b16 v[236:237], v201 offset:10240
	s_waitcnt lgkmcnt(6)
	v_mfma_f32_32x32x16_bf16 v[96:111], v[124:127], v[132:135], v[96:111]
	v_exp_f32_e32 v215, v86
	v_exp_f32_e32 v216, v87
	v_cvt_pk_bf16_f32 v158, v213, v214
	v_cvt_pk_bf16_f32 v159, v215, v216
	ds_read_b64_tr_b16 v[238:239], v203 offset:8192
	ds_read_b64_tr_b16 v[240:241], v203 offset:10240
	s_waitcnt lgkmcnt(6)
	v_mfma_f32_32x32x16_bf16 v[64:79], v[226:229], v[156:159], v[64:79]
	v_exp_f32_e32 v217, v88
	v_exp_f32_e32 v218, v89
	ds_read_b64_tr_b16 v[242:243], v198 offset:12288
	ds_read_b64_tr_b16 v[244:245], v198 offset:14336
	s_waitcnt lgkmcnt(6)
	v_mfma_f32_32x32x16_bf16 v[48:63], v[230:233], v[156:159], v[48:63]
	v_exp_f32_e32 v219, v90
	v_exp_f32_e32 v220, v91
	v_cvt_pk_bf16_f32 v160, v217, v218
	ds_read_b64_tr_b16 v[246:247], v199 offset:12288
	ds_read_b64_tr_b16 v[248:249], v199 offset:14336
	s_waitcnt lgkmcnt(6)
	v_mfma_f32_32x32x16_bf16 v[32:47], v[234:237], v[156:159], v[32:47]
	v_exp_f32_e32 v221, v92
	v_exp_f32_e32 v222, v93
	v_cvt_pk_bf16_f32 v161, v219, v220
	ds_read_b64_tr_b16 v[226:227], v201 offset:12288
	ds_read_b64_tr_b16 v[228:229], v201 offset:14336
	s_waitcnt lgkmcnt(6)
	v_mfma_f32_32x32x16_bf16 v[16:31], v[238:241], v[156:159], v[16:31]
	v_exp_f32_e32 v223, v94
	v_exp_f32_e32 v224, v95
	v_cvt_pk_bf16_f32 v162, v221, v222
	v_cvt_pk_bf16_f32 v163, v223, v224
	ds_read_b64_tr_b16 v[230:231], v203 offset:12288
	ds_read_b64_tr_b16 v[232:233], v203 offset:14336
	s_waitcnt lgkmcnt(6)
	v_mfma_f32_32x32x16_bf16 v[64:79], v[242:245], v[160:163], v[64:79]
	v_add_f32_e32 v225, v225, v209
	v_add_f32_e32 v166, v166, v210
	v_add_f32_e32 v175, v175, v211
	v_add_f32_e32 v202, v202, v212
	ds_read_b128 v[112:115], v180 offset:40960
	s_waitcnt lgkmcnt(5)
	v_mfma_f32_32x32x16_bf16 v[48:63], v[246:249], v[160:163], v[48:63]
	v_add_f32_e32 v225, v225, v213
	v_add_f32_e32 v166, v166, v214
	v_add_f32_e32 v175, v175, v215
	v_add_f32_e32 v202, v202, v216
	ds_read_b128 v[116:119], v189 offset:40960
	s_waitcnt lgkmcnt(4)
	v_mfma_f32_32x32x16_bf16 v[32:47], v[226:229], v[160:163], v[32:47]
	v_add_f32_e32 v225, v225, v217
	v_add_f32_e32 v166, v166, v218
	v_add_f32_e32 v175, v175, v219
	v_add_f32_e32 v202, v202, v220
	ds_read_b128 v[120:123], v191 offset:40960
	s_waitcnt lgkmcnt(3)
	v_mfma_f32_32x32x16_bf16 v[16:31], v[230:233], v[160:163], v[16:31]
	v_add_f32_e32 v225, v225, v221
	v_add_f32_e32 v166, v166, v222
	v_add_f32_e32 v175, v175, v223
	v_add_f32_e32 v202, v202, v224
	ds_read_b128 v[124:127], v192 offset:40960
	s_waitcnt lgkmcnt(3)
	v_mfma_f32_32x32x16_bf16 v[80:95], v[112:115], v[140:143], v[0:15]
	v_exp_f32_e32 v209, v96
	v_exp_f32_e32 v210, v97
	ds_read_b64_tr_b16 v[234:235], v198 offset:32768
	ds_read_b64_tr_b16 v[236:237], v198 offset:34816
	s_waitcnt lgkmcnt(4)
	v_mfma_f32_32x32x16_bf16 v[80:95], v[116:119], v[144:147], v[80:95]
	v_exp_f32_e32 v211, v98
	v_exp_f32_e32 v212, v99
	v_cvt_pk_bf16_f32 v148, v209, v210
	ds_read_b64_tr_b16 v[238:239], v199 offset:32768
	ds_read_b64_tr_b16 v[240:241], v199 offset:34816
	s_waitcnt lgkmcnt(5)
	v_mfma_f32_32x32x16_bf16 v[80:95], v[120:123], v[136:139], v[80:95]
	v_exp_f32_e32 v213, v100
	v_exp_f32_e32 v214, v101
	v_cvt_pk_bf16_f32 v149, v211, v212
	ds_read_b64_tr_b16 v[242:243], v201 offset:32768
	ds_read_b64_tr_b16 v[244:245], v201 offset:34816
	s_waitcnt lgkmcnt(6)
	v_mfma_f32_32x32x16_bf16 v[80:95], v[124:127], v[132:135], v[80:95]
	v_exp_f32_e32 v215, v102
	v_exp_f32_e32 v216, v103
	v_cvt_pk_bf16_f32 v150, v213, v214
	v_cvt_pk_bf16_f32 v151, v215, v216
	ds_read_b64_tr_b16 v[246:247], v203 offset:32768
	ds_read_b64_tr_b16 v[248:249], v203 offset:34816
	s_waitcnt lgkmcnt(6)
	v_mfma_f32_32x32x16_bf16 v[64:79], v[234:237], v[148:151], v[64:79]
	v_exp_f32_e32 v217, v104
	v_exp_f32_e32 v218, v105
	ds_read_b64_tr_b16 v[226:227], v198 offset:36864
	ds_read_b64_tr_b16 v[228:229], v198 offset:38912
	s_waitcnt lgkmcnt(6)
	v_mfma_f32_32x32x16_bf16 v[48:63], v[238:241], v[148:151], v[48:63]
	v_exp_f32_e32 v219, v106
	v_exp_f32_e32 v220, v107
	v_cvt_pk_bf16_f32 v152, v217, v218
	ds_read_b64_tr_b16 v[230:231], v199 offset:36864
	ds_read_b64_tr_b16 v[232:233], v199 offset:38912
	s_waitcnt lgkmcnt(6)
	v_mfma_f32_32x32x16_bf16 v[32:47], v[242:245], v[148:151], v[32:47]
	v_exp_f32_e32 v221, v108
	v_exp_f32_e32 v222, v109
	v_cvt_pk_bf16_f32 v153, v219, v220
	ds_read_b64_tr_b16 v[234:235], v201 offset:36864
	ds_read_b64_tr_b16 v[236:237], v201 offset:38912
	s_waitcnt lgkmcnt(6)
	v_mfma_f32_32x32x16_bf16 v[16:31], v[246:249], v[148:151], v[16:31]
	v_exp_f32_e32 v223, v110
	v_exp_f32_e32 v224, v111
	v_cvt_pk_bf16_f32 v154, v221, v222
	v_cvt_pk_bf16_f32 v155, v223, v224
	ds_read_b64_tr_b16 v[238:239], v203 offset:36864
	ds_read_b64_tr_b16 v[240:241], v203 offset:38912
	s_waitcnt lgkmcnt(6)
	v_mfma_f32_32x32x16_bf16 v[64:79], v[226:229], v[152:155], v[64:79]
	s_waitcnt vmcnt(4)
	s_barrier
	s_and_b32 s1, s35, 3
	s_add_i32 s35, s35, 1
	s_cmp_lg_u32 s1, 0
	s_cbranch_scc1 .Latt_bs_3
	v_lshlrev_b32_e32 v204, 16, v194
	v_and_b32_e32 v205, 0xffff0000, v194
	v_fma_f32 v182, v174, v182, v204
	v_fma_f32 v183, v174, v183, v205
	s_lshr_b32 s1, s35, 2
	s_add_i32 s1, s1, 1
	s_cmpk_lt_u32 s1, 0x84
	s_cbranch_scc0 .Latt_bs_3
	s_lshl_b32 s2, s1, 14
	s_mov_b32 s3, 0
	s_lshl_b32 s4, s1, 8
	s_mov_b32 s5, 0
	v_lshl_add_u64 v[204:205], v[168:169], 0, s[2:3]
	v_lshl_add_u64 v[196:197], v[170:171], 0, s[4:5]
	v_cvt_pk_bf16_f32 v206, v182, v183
	global_load_dword v194, v[204:205], off
	global_load_dword v174, v[196:197], off
	global_store_dword v[204:205], v206, off
.Latt_bs_3:
	v_add_f32_e32 v225, v225, v209
	v_add_f32_e32 v166, v166, v210
	v_add_f32_e32 v175, v175, v211
	v_add_f32_e32 v202, v202, v212
	s_add_i32 m0, s17, 65536
	ds_read_b128 v[112:115], v178
	global_load_lds_dwordx4 v181, s[36:37]
	s_waitcnt lgkmcnt(5)
	v_mfma_f32_32x32x16_bf16 v[48:63], v[230:233], v[152:155], v[48:63]
	v_add_f32_e32 v225, v225, v213
	v_add_f32_e32 v166, v166, v214
	v_add_f32_e32 v175, v175, v215
	v_add_f32_e32 v202, v202, v216
	s_add_i32 m0, s17, 66560
	ds_read_b128 v[116:119], v128
	global_load_lds_dwordx4 v165, s[36:37]
	s_waitcnt lgkmcnt(4)
	v_mfma_f32_32x32x16_bf16 v[32:47], v[234:237], v[152:155], v[32:47]
	v_add_f32_e32 v225, v225, v217
	v_add_f32_e32 v166, v166, v218
	v_add_f32_e32 v175, v175, v219
	v_add_f32_e32 v202, v202, v220
	s_add_i32 m0, s17, 81920
	ds_read_b128 v[120:123], v130
	global_load_lds_dwordx4 v207, s[36:37]
	s_waitcnt lgkmcnt(3)
	v_mfma_f32_32x32x16_bf16 v[16:31], v[238:241], v[152:155], v[16:31]
	v_add_f32_e32 v225, v225, v221
	v_add_f32_e32 v166, v166, v222
	v_add_f32_e32 v175, v175, v223
	v_add_f32_e32 v202, v202, v224
	s_add_i32 m0, s17, 82944
	ds_read_b128 v[124:127], v131
	global_load_lds_dwordx4 v208, s[36:37]
	s_add_u32 s36, s36, 0x68000
	s_addc_u32 s37, s37, 0
	s_cmp_eq_u32 s16, 0
	s_cselect_b32 s36, s38, s36
	s_cselect_b32 s37, s39, s37
	s_add_i32 s16, s16, 1
	s_cmpk_lt_u32 s16, 0x84
	s_cbranch_scc1 .Latt_loop
	ds_read_b64_tr_b16 v[226:227], v198 offset:40960
	ds_read_b64_tr_b16 v[228:229], v198 offset:43008
	ds_read_b64_tr_b16 v[230:231], v199 offset:40960
	ds_read_b64_tr_b16 v[232:233], v199 offset:43008
	ds_read_b64_tr_b16 v[234:235], v201 offset:40960
	ds_read_b64_tr_b16 v[236:237], v201 offset:43008
	ds_read_b64_tr_b16 v[238:239], v203 offset:40960
	ds_read_b64_tr_b16 v[240:241], v203 offset:43008
	ds_read_b64_tr_b16 v[242:243], v198 offset:45056
	ds_read_b64_tr_b16 v[244:245], v198 offset:47104
	ds_read_b64_tr_b16 v[246:247], v199 offset:45056
	ds_read_b64_tr_b16 v[248:249], v199 offset:47104
	ds_read_b64_tr_b16 v[112:113], v201 offset:45056
	ds_read_b64_tr_b16 v[114:115], v201 offset:47104
	ds_read_b64_tr_b16 v[120:121], v203 offset:45056
	ds_read_b64_tr_b16 v[122:123], v203 offset:47104
	v_exp_f32_e32 v209, v80
	v_exp_f32_e32 v210, v81
	v_exp_f32_e32 v211, v82
	v_exp_f32_e32 v212, v83
	v_exp_f32_e32 v213, v84
	v_exp_f32_e32 v214, v85
	v_exp_f32_e32 v215, v86
	v_exp_f32_e32 v216, v87
	v_exp_f32_e32 v217, v88
	v_exp_f32_e32 v218, v89
	v_exp_f32_e32 v219, v90
	v_exp_f32_e32 v220, v91
	v_exp_f32_e32 v221, v92
	v_exp_f32_e32 v222, v93
	v_exp_f32_e32 v223, v94
	v_exp_f32_e32 v224, v95
	s_nop 0
	v_cvt_pk_bf16_f32 v156, v209, v210
	v_cvt_pk_bf16_f32 v157, v211, v212
	v_cvt_pk_bf16_f32 v158, v213, v214
	v_cvt_pk_bf16_f32 v159, v215, v216
	v_cvt_pk_bf16_f32 v160, v217, v218
	v_cvt_pk_bf16_f32 v161, v219, v220
	v_cvt_pk_bf16_f32 v162, v221, v222
	v_cvt_pk_bf16_f32 v163, v223, v224
	v_add_f32_e32 v225, v225, v209
	v_add_f32_e32 v166, v166, v210
	v_add_f32_e32 v175, v175, v211
	v_add_f32_e32 v202, v202, v212
	v_add_f32_e32 v225, v225, v213
	v_add_f32_e32 v166, v166, v214
	v_add_f32_e32 v175, v175, v215
	v_add_f32_e32 v202, v202, v216
	v_add_f32_e32 v225, v225, v217
	v_add_f32_e32 v166, v166, v218
	v_add_f32_e32 v175, v175, v219
	v_add_f32_e32 v202, v202, v220
	v_add_f32_e32 v225, v225, v221
	v_add_f32_e32 v166, v166, v222
	v_add_f32_e32 v175, v175, v223
	v_add_f32_e32 v202, v202, v224
	s_waitcnt lgkmcnt(0)
	v_mfma_f32_32x32x16_bf16 v[64:79], v[226:229], v[156:159], v[64:79]
	v_mfma_f32_32x32x16_bf16 v[48:63], v[230:233], v[156:159], v[48:63]
	v_mfma_f32_32x32x16_bf16 v[32:47], v[234:237], v[156:159], v[32:47]
	v_mfma_f32_32x32x16_bf16 v[16:31], v[238:241], v[156:159], v[16:31]
	v_mfma_f32_32x32x16_bf16 v[64:79], v[242:245], v[160:163], v[64:79]
	v_mfma_f32_32x32x16_bf16 v[48:63], v[246:249], v[160:163], v[48:63]
	v_mfma_f32_32x32x16_bf16 v[32:47], v[112:115], v[160:163], v[32:47]
	v_mfma_f32_32x32x16_bf16 v[16:31], v[120:123], v[160:163], v[16:31]
	v_add_f32_e32 v225, v225, v166
	v_add_f32_e32 v175, v175, v202
	v_add_f32_e32 v80, v225, v175
	v_and_b32_e32 v196, 63, v188
	s_cmpk_lt_u32 s34, 0x100
	s_cselect_b64 s[4:5], -1, 0
	s_lshl_b32 s0, s31, 14
	s_waitcnt vmcnt(0)
	s_barrier
	ds_bpermute_b32 v81, v195, v80
	s_nop 7
	s_nop 7
	s_cmp_eq_u32 s30, 1
	s_waitcnt lgkmcnt(0)
	v_add_f32_e32 v80, v80, v81
	v_cndmask_b32_e64 v81, v164, 1.0, s[4:5]
	v_div_scale_f32 v82, s[16:17], v80, v80, v81
	v_rcp_f32_e32 v83, v82
	s_nop 0
	v_fma_f32 v84, -v82, v83, 1.0
	v_fmac_f32_e32 v83, v84, v83
	v_div_scale_f32 v84, vcc, v81, v80, v81
	v_mul_f32_e32 v85, v84, v83
	v_fma_f32 v86, -v82, v85, v84
	v_fmac_f32_e32 v85, v86, v83
	v_fma_f32 v82, -v82, v85, v84
	v_div_fmas_f32 v82, v82, v83, v85
	v_div_fixup_f32 v92, v82, v80, v81
	v_pk_mul_f32 v[88:89], v[64:65], v[92:93] op_sel_hi:[1,0]
	v_pk_mul_f32 v[90:91], v[66:67], v[92:93] op_sel_hi:[1,0]
	v_pk_mul_f32 v[82:83], v[68:69], v[92:93] op_sel_hi:[1,0]
	v_pk_mul_f32 v[86:87], v[70:71], v[92:93] op_sel_hi:[1,0]
	v_pk_mul_f32 v[80:81], v[72:73], v[92:93] op_sel_hi:[1,0]
	v_pk_mul_f32 v[84:85], v[74:75], v[92:93] op_sel_hi:[1,0]
	v_pk_mul_f32 v[72:73], v[76:77], v[92:93] op_sel_hi:[1,0]
	v_pk_mul_f32 v[78:79], v[78:79], v[92:93] op_sel_hi:[1,0]
	v_pk_mul_f32 v[68:69], v[48:49], v[92:93] op_sel_hi:[1,0]
	v_pk_mul_f32 v[76:77], v[50:51], v[92:93] op_sel_hi:[1,0]
	v_pk_mul_f32 v[66:67], v[52:53], v[92:93] op_sel_hi:[1,0]
	v_pk_mul_f32 v[74:75], v[54:55], v[92:93] op_sel_hi:[1,0]
	v_pk_mul_f32 v[64:65], v[56:57], v[92:93] op_sel_hi:[1,0]
	v_pk_mul_f32 v[70:71], v[58:59], v[92:93] op_sel_hi:[1,0]
	v_pk_mul_f32 v[54:55], v[60:61], v[92:93] op_sel_hi:[1,0]
	v_pk_mul_f32 v[60:61], v[62:63], v[92:93] op_sel_hi:[1,0]
	v_pk_mul_f32 v[50:51], v[32:33], v[92:93] op_sel_hi:[1,0]
	v_pk_mul_f32 v[58:59], v[34:35], v[92:93] op_sel_hi:[1,0]
	v_pk_mul_f32 v[48:49], v[36:37], v[92:93] op_sel_hi:[1,0]
	v_pk_mul_f32 v[56:57], v[38:39], v[92:93] op_sel_hi:[1,0]
	v_pk_mul_f32 v[40:41], v[40:41], v[92:93] op_sel_hi:[1,0]
	v_pk_mul_f32 v[52:53], v[42:43], v[92:93] op_sel_hi:[1,0]
	v_pk_mul_f32 v[36:37], v[44:45], v[92:93] op_sel_hi:[1,0]
	v_pk_mul_f32 v[44:45], v[46:47], v[92:93] op_sel_hi:[1,0]
	v_pk_mul_f32 v[34:35], v[16:17], v[92:93] op_sel_hi:[1,0]
	v_pk_mul_f32 v[42:43], v[18:19], v[92:93] op_sel_hi:[1,0]
	v_pk_mul_f32 v[32:33], v[20:21], v[92:93] op_sel_hi:[1,0]
	v_pk_mul_f32 v[38:39], v[22:23], v[92:93] op_sel_hi:[1,0]
	v_pk_mul_f32 v[20:21], v[24:25], v[92:93] op_sel_hi:[1,0]
	v_pk_mul_f32 v[22:23], v[26:27], v[92:93] op_sel_hi:[1,0]
	v_pk_mul_f32 v[16:17], v[28:29], v[92:93] op_sel_hi:[1,0]
	v_pk_mul_f32 v[18:19], v[30:31], v[92:93] op_sel_hi:[1,0]
	v_lshl_add_u32 v24, v196, 2, s0
	s_cbranch_scc0 .LBB0_446
	ds_write2st64_b32 v24, v88, v89 offset1:1
	ds_write2st64_b32 v24, v90, v91 offset0:2 offset1:3
	ds_write2st64_b32 v24, v82, v83 offset0:4 offset1:5
	ds_write2st64_b32 v24, v86, v87 offset0:6 offset1:7
	ds_write2st64_b32 v24, v80, v81 offset0:8 offset1:9
	ds_write2st64_b32 v24, v84, v85 offset0:10 offset1:11
	ds_write2st64_b32 v24, v72, v73 offset0:12 offset1:13
	ds_write2st64_b32 v24, v78, v79 offset0:14 offset1:15
	ds_write2st64_b32 v24, v68, v69 offset0:16 offset1:17
	ds_write2st64_b32 v24, v76, v77 offset0:18 offset1:19
	ds_write2st64_b32 v24, v66, v67 offset0:20 offset1:21
	ds_write2st64_b32 v24, v74, v75 offset0:22 offset1:23
	ds_write2st64_b32 v24, v64, v65 offset0:24 offset1:25
	ds_write2st64_b32 v24, v70, v71 offset0:26 offset1:27
	ds_write2st64_b32 v24, v54, v55 offset0:28 offset1:29
	ds_write2st64_b32 v24, v60, v61 offset0:30 offset1:31
	ds_write2st64_b32 v24, v50, v51 offset0:32 offset1:33
	ds_write2st64_b32 v24, v58, v59 offset0:34 offset1:35
	ds_write2st64_b32 v24, v48, v49 offset0:36 offset1:37
	ds_write2st64_b32 v24, v56, v57 offset0:38 offset1:39
	ds_write2st64_b32 v24, v40, v41 offset0:40 offset1:41
	ds_write2st64_b32 v24, v52, v53 offset0:42 offset1:43
	ds_write2st64_b32 v24, v36, v37 offset0:44 offset1:45
	ds_write2st64_b32 v24, v44, v45 offset0:46 offset1:47
	ds_write2st64_b32 v24, v34, v35 offset0:48 offset1:49
	ds_write2st64_b32 v24, v42, v43 offset0:50 offset1:51
	ds_write2st64_b32 v24, v32, v33 offset0:52 offset1:53
	ds_write2st64_b32 v24, v38, v39 offset0:54 offset1:55
	ds_write2st64_b32 v24, v20, v21 offset0:56 offset1:57
	ds_write2st64_b32 v24, v22, v23 offset0:58 offset1:59
	ds_write2st64_b32 v24, v16, v17 offset0:60 offset1:61
	ds_write2st64_b32 v24, v18, v19 offset0:62 offset1:63
.LBB0_446:
	s_andn2_b64 vcc, exec, s[4:5]
	s_waitcnt lgkmcnt(0)
	s_barrier
	s_cbranch_vccnz .LBB0_427
	ds_read2st64_b32 v[26:27], v24 offset1:1
	ds_read2st64_b32 v[28:29], v24 offset0:2 offset1:3
	ds_read2st64_b32 v[30:31], v24 offset0:4 offset1:5
	ds_read2st64_b32 v[46:47], v24 offset0:6 offset1:7
	ds_read2st64_b32 v[62:63], v24 offset0:8 offset1:9
	ds_read2st64_b32 v[96:97], v24 offset0:10 offset1:11
	ds_read2st64_b32 v[98:99], v24 offset0:12 offset1:13
	ds_read2st64_b32 v[100:101], v24 offset0:14 offset1:15
	ds_read2st64_b32 v[102:103], v24 offset0:16 offset1:17
	ds_read2st64_b32 v[104:105], v24 offset0:18 offset1:19
	ds_read2st64_b32 v[106:107], v24 offset0:20 offset1:21
	ds_read2st64_b32 v[108:109], v24 offset0:22 offset1:23
	ds_read2st64_b32 v[110:111], v24 offset0:24 offset1:25
	ds_read2st64_b32 v[114:115], v24 offset0:26 offset1:27
	ds_read2st64_b32 v[116:117], v24 offset0:28 offset1:29
	ds_read2st64_b32 v[118:119], v24 offset0:30 offset1:31
	ds_read2st64_b32 v[120:121], v24 offset0:32 offset1:33
	ds_read2st64_b32 v[122:123], v24 offset0:34 offset1:35
	ds_read2st64_b32 v[124:125], v24 offset0:36 offset1:37
	ds_read2st64_b32 v[126:127], v24 offset0:38 offset1:39
	ds_read2st64_b32 v[132:133], v24 offset0:40 offset1:41
	ds_read2st64_b32 v[134:135], v24 offset0:42 offset1:43
	ds_read2st64_b32 v[136:137], v24 offset0:44 offset1:45
	ds_read2st64_b32 v[138:139], v24 offset0:46 offset1:47
	ds_read2st64_b32 v[140:141], v24 offset0:56 offset1:57
	ds_read2st64_b32 v[142:143], v24 offset0:58 offset1:59
	ds_read2st64_b32 v[92:93], v24 offset0:60 offset1:61
	ds_read2st64_b32 v[94:95], v24 offset0:62 offset1:63
	ds_read2st64_b32 v[144:145], v24 offset0:48 offset1:49
	ds_read2st64_b32 v[146:147], v24 offset0:50 offset1:51
	ds_read2st64_b32 v[150:151], v24 offset0:52 offset1:53
	ds_read2st64_b32 v[24:25], v24 offset0:54 offset1:55
	s_waitcnt lgkmcnt(14)
	v_pk_add_f32 v[88:89], v[88:89], v[26:27] neg_lo:[0,1] neg_hi:[0,1]
	v_lshlrev_b32_e32 v175, 2, v179
	v_pk_add_f32 v[90:91], v[90:91], v[28:29] neg_lo:[0,1] neg_hi:[0,1]
	v_pk_mul_f32 v[158:159], v[88:89], v[88:89]
	s_waitcnt lgkmcnt(5)
	v_pk_add_f32 v[16:17], v[16:17], v[92:93] neg_lo:[0,1] neg_hi:[0,1]
	s_waitcnt lgkmcnt(4)
	v_pk_add_f32 v[18:19], v[18:19], v[94:95] neg_lo:[0,1] neg_hi:[0,1]
	global_load_dwordx4 v[92:95], v175, s[70:71]
	global_load_dwordx4 v[198:201], v175, s[70:71] offset:32
	global_load_dwordx4 v[202:205], v175, s[70:71] offset:64
	global_load_dwordx4 v[206:209], v175, s[70:71] offset:96
	global_load_dwordx4 v[210:213], v175, s[70:71] offset:128
	global_load_dwordx4 v[214:217], v175, s[70:71] offset:160
	global_load_dwordx4 v[218:221], v175, s[70:71] offset:192
	global_load_dwordx4 v[222:225], v175, s[70:71] offset:224
	global_load_dwordx4 v[226:229], v175, s[70:71] offset:256
	global_load_dwordx4 v[230:233], v175, s[70:71] offset:288
	global_load_dwordx4 v[234:237], v175, s[70:71] offset:320
	global_load_dwordx4 v[238:241], v175, s[70:71] offset:352
	global_load_dwordx4 v[242:245], v175, s[70:71] offset:384
	global_load_dwordx4 v[246:249], v175, s[70:71] offset:416
	global_load_dwordx4 v[184:187], v175, s[70:71] offset:448
	global_load_dwordx4 v[128:131], v175, s[70:71] offset:480
	v_pk_mul_f32 v[156:157], v[90:91], v[90:91]
	v_pk_add_f32 v[22:23], v[22:23], v[142:143] neg_lo:[0,1] neg_hi:[0,1]
	v_add_f32_e32 v142, v158, v159
	v_pk_add_f32 v[82:83], v[82:83], v[30:31] neg_lo:[0,1] neg_hi:[0,1]
	v_add_f32_e32 v142, v142, v156
	v_pk_mul_f32 v[162:163], v[82:83], v[82:83]
	v_add_f32_e32 v142, v142, v157
	v_pk_add_f32 v[86:87], v[86:87], v[46:47] neg_lo:[0,1] neg_hi:[0,1]
	v_add_f32_e32 v142, v142, v162
	v_pk_mul_f32 v[160:161], v[86:87], v[86:87]
	v_add_f32_e32 v142, v142, v163
	v_pk_add_f32 v[62:63], v[80:81], v[62:63] neg_lo:[0,1] neg_hi:[0,1]
	v_add_f32_e32 v142, v142, v160
	v_pk_mul_f32 v[80:81], v[62:63], v[62:63]
	v_add_f32_e32 v142, v142, v161
	v_pk_add_f32 v[84:85], v[84:85], v[96:97] neg_lo:[0,1] neg_hi:[0,1]
	v_add_f32_e32 v80, v142, v80
	v_pk_mul_f32 v[96:97], v[84:85], v[84:85]
	v_add_f32_e32 v80, v80, v81
	v_pk_add_f32 v[72:73], v[72:73], v[98:99] neg_lo:[0,1] neg_hi:[0,1]
	v_add_f32_e32 v80, v80, v96
	v_pk_mul_f32 v[98:99], v[72:73], v[72:73]
	v_add_f32_e32 v80, v80, v97
	v_pk_add_f32 v[78:79], v[78:79], v[100:101] neg_lo:[0,1] neg_hi:[0,1]
	v_add_f32_e32 v80, v80, v98
	v_pk_mul_f32 v[100:101], v[78:79], v[78:79]
	v_add_f32_e32 v80, v80, v99
	v_pk_add_f32 v[68:69], v[68:69], v[102:103] neg_lo:[0,1] neg_hi:[0,1]
	v_add_f32_e32 v80, v80, v100
	v_pk_mul_f32 v[102:103], v[68:69], v[68:69]
	v_add_f32_e32 v80, v80, v101
	v_pk_add_f32 v[76:77], v[76:77], v[104:105] neg_lo:[0,1] neg_hi:[0,1]
	v_add_f32_e32 v80, v80, v102
	v_pk_mul_f32 v[104:105], v[76:77], v[76:77]
	v_add_f32_e32 v80, v80, v103
	v_pk_add_f32 v[66:67], v[66:67], v[106:107] neg_lo:[0,1] neg_hi:[0,1]
	v_add_f32_e32 v80, v80, v104
	v_pk_mul_f32 v[106:107], v[66:67], v[66:67]
	v_add_f32_e32 v80, v80, v105
	v_pk_add_f32 v[74:75], v[74:75], v[108:109] neg_lo:[0,1] neg_hi:[0,1]
	v_add_f32_e32 v80, v80, v106
	v_pk_mul_f32 v[108:109], v[74:75], v[74:75]
	v_add_f32_e32 v80, v80, v107
	v_pk_add_f32 v[64:65], v[64:65], v[110:111] neg_lo:[0,1] neg_hi:[0,1]
	v_add_f32_e32 v80, v80, v108
	v_pk_mul_f32 v[110:111], v[64:65], v[64:65]
	v_add_f32_e32 v80, v80, v109
	v_pk_add_f32 v[70:71], v[70:71], v[114:115] neg_lo:[0,1] neg_hi:[0,1]
	v_add_f32_e32 v80, v80, v110
	v_pk_mul_f32 v[114:115], v[70:71], v[70:71]
	v_add_f32_e32 v80, v80, v111
	v_pk_add_f32 v[54:55], v[54:55], v[116:117] neg_lo:[0,1] neg_hi:[0,1]
	v_add_f32_e32 v80, v80, v114
	v_pk_mul_f32 v[116:117], v[54:55], v[54:55]
	v_add_f32_e32 v80, v80, v115
	v_pk_add_f32 v[60:61], v[60:61], v[118:119] neg_lo:[0,1] neg_hi:[0,1]
	v_add_f32_e32 v80, v80, v116
	v_pk_mul_f32 v[118:119], v[60:61], v[60:61]
	v_add_f32_e32 v80, v80, v117
	v_pk_add_f32 v[50:51], v[50:51], v[120:121] neg_lo:[0,1] neg_hi:[0,1]
	v_add_f32_e32 v80, v80, v118
	v_pk_mul_f32 v[120:121], v[50:51], v[50:51]
	v_add_f32_e32 v80, v80, v119
	v_pk_add_f32 v[58:59], v[58:59], v[122:123] neg_lo:[0,1] neg_hi:[0,1]
	v_add_f32_e32 v80, v80, v120
	v_pk_mul_f32 v[122:123], v[58:59], v[58:59]
	v_add_f32_e32 v80, v80, v121
	v_pk_add_f32 v[48:49], v[48:49], v[124:125] neg_lo:[0,1] neg_hi:[0,1]
	v_add_f32_e32 v80, v80, v122
	v_pk_mul_f32 v[124:125], v[48:49], v[48:49]
	v_add_f32_e32 v80, v80, v123
	v_pk_add_f32 v[56:57], v[56:57], v[126:127] neg_lo:[0,1] neg_hi:[0,1]
	v_add_f32_e32 v80, v80, v124
	v_pk_mul_f32 v[126:127], v[56:57], v[56:57]
	v_add_f32_e32 v80, v80, v125
	v_pk_add_f32 v[132:133], v[40:41], v[132:133] neg_lo:[0,1] neg_hi:[0,1]
	v_add_f32_e32 v80, v80, v126
	v_pk_mul_f32 v[40:41], v[132:133], v[132:133]
	v_add_f32_e32 v80, v80, v127
	v_pk_add_f32 v[46:47], v[52:53], v[134:135] neg_lo:[0,1] neg_hi:[0,1]
	v_add_f32_e32 v40, v80, v40
	v_pk_mul_f32 v[52:53], v[46:47], v[46:47]
	v_add_f32_e32 v40, v40, v41
	v_pk_add_f32 v[36:37], v[36:37], v[136:137] neg_lo:[0,1] neg_hi:[0,1]
	v_add_f32_e32 v40, v40, v52
	v_pk_mul_f32 v[134:135], v[36:37], v[36:37]
	v_add_f32_e32 v40, v40, v53
	v_pk_add_f32 v[30:31], v[44:45], v[138:139] neg_lo:[0,1] neg_hi:[0,1]
	v_add_f32_e32 v40, v40, v134
	v_pk_mul_f32 v[44:45], v[30:31], v[30:31]
	v_add_f32_e32 v40, v40, v135
	s_waitcnt lgkmcnt(3)
	v_pk_add_f32 v[34:35], v[34:35], v[144:145] neg_lo:[0,1] neg_hi:[0,1]
	v_add_f32_e32 v40, v40, v44
	v_pk_mul_f32 v[136:137], v[34:35], v[34:35]
	v_add_f32_e32 v40, v40, v45
	s_waitcnt lgkmcnt(2)
	v_pk_add_f32 v[26:27], v[42:43], v[146:147] neg_lo:[0,1] neg_hi:[0,1]
	v_add_f32_e32 v40, v40, v136
	v_pk_mul_f32 v[42:43], v[26:27], v[26:27]
	v_add_f32_e32 v40, v40, v137
	s_waitcnt lgkmcnt(1)
	v_pk_add_f32 v[28:29], v[32:33], v[150:151] neg_lo:[0,1] neg_hi:[0,1]
	v_add_f32_e32 v40, v40, v42
	v_pk_mul_f32 v[32:33], v[28:29], v[28:29]
	v_add_f32_e32 v40, v40, v43
	s_waitcnt lgkmcnt(0)
	v_pk_add_f32 v[24:25], v[38:39], v[24:25] neg_lo:[0,1] neg_hi:[0,1]
	v_add_f32_e32 v32, v40, v32
	v_pk_mul_f32 v[38:39], v[24:25], v[24:25]
	v_add_f32_e32 v32, v32, v33
	v_pk_add_f32 v[20:21], v[20:21], v[140:141] neg_lo:[0,1] neg_hi:[0,1]
	v_add_f32_e32 v32, v32, v38
	v_pk_mul_f32 v[140:141], v[20:21], v[20:21]
	v_add_f32_e32 v32, v32, v39
	v_add_f32_e32 v32, v32, v140
	v_pk_mul_f32 v[138:139], v[22:23], v[22:23]
	v_add_f32_e32 v32, v32, v141
	v_add_f32_e32 v32, v32, v138
	v_pk_mul_f32 v[152:153], v[16:17], v[16:17]
	v_add_f32_e32 v32, v32, v139
	v_add_f32_e32 v32, v32, v152
	v_pk_mul_f32 v[154:155], v[18:19], v[18:19]
	v_add_f32_e32 v32, v32, v153
	v_add_f32_e32 v32, v32, v154
	v_add_f32_e32 v38, v32, v155
	ds_bpermute_b32 v39, v195, v38
	v_lshlrev_b64 v[32:33], 11, v[176:177]
	v_lshl_add_u64 v[32:33], s[74:75], 0, v[32:33]
	v_lshl_add_u64 v[32:33], v[32:33], 0, s[12:13]
	v_lshlrev_b32_e32 v166, 1, v179
	s_waitcnt lgkmcnt(0)
	v_add_f32_e32 v38, v38, v39
	v_fmamk_f32 v38, v38, 0x3c000000, v193
	v_mul_f32_e32 v39, 0x4b800000, v38
	v_cmp_gt_f32_e32 vcc, s27, v38
	v_lshl_add_u64 v[32:33], v[32:33], 0, v[166:167]
	v_lshl_add_u64 v[44:45], v[32:33], 0, s[14:15]
	v_cndmask_b32_e32 v38, v38, v39, vcc
	v_rsq_f32_e32 v38, v38
	s_nop 0
	v_mul_f32_e32 v39, 0x45800000, v38
	v_cndmask_b32_e32 v38, v38, v39, vcc
	v_mul_f32_e32 v42, 0x3f4ccccd, v38
	v_pk_mul_f32 v[38:39], v[88:89], v[42:43] op_sel_hi:[1,0]
	v_pk_mul_f32 v[40:41], v[90:91], v[42:43] op_sel_hi:[1,0]
	s_waitcnt vmcnt(0)
	v_pk_mul_f32 v[38:39], v[92:93], v[38:39]
	v_pk_mul_f32 v[40:41], v[94:95], v[40:41]
	v_cvt_pk_bf16_f32 v38, v38, v39
	v_cvt_pk_bf16_f32 v39, v40, v41
	v_add_co_u32_e32 v40, vcc, s29, v32
	v_pk_mul_f32 v[52:53], v[84:85], v[42:43] op_sel_hi:[1,0]
	s_nop 0
	v_addc_co_u32_e32 v41, vcc, 0, v33, vcc
	global_store_dwordx2 v[40:41], v[38:39], off offset:1024
	v_pk_mul_f32 v[32:33], v[82:83], v[42:43] op_sel_hi:[1,0]
	v_pk_mul_f32 v[46:47], v[46:47], v[42:43] op_sel_hi:[1,0]
	v_pk_mul_f32 v[30:31], v[30:31], v[42:43] op_sel_hi:[1,0]
	v_pk_mul_f32 v[34:35], v[34:35], v[42:43] op_sel_hi:[1,0]
	v_pk_mul_f32 v[26:27], v[26:27], v[42:43] op_sel_hi:[1,0]
	v_pk_mul_f32 v[24:25], v[24:25], v[42:43] op_sel_hi:[1,0]
	v_pk_mul_f32 v[20:21], v[20:21], v[42:43] op_sel_hi:[1,0]
	v_pk_mul_f32 v[22:23], v[22:23], v[42:43] op_sel_hi:[1,0]
	v_pk_mul_f32 v[16:17], v[16:17], v[42:43] op_sel_hi:[1,0]
	v_pk_mul_f32 v[18:19], v[18:19], v[42:43] op_sel_hi:[1,0]
	v_pk_mul_f32 v[32:33], v[198:199], v[32:33]
	v_pk_mul_f32 v[38:39], v[86:87], v[42:43] op_sel_hi:[1,0]
	v_cvt_pk_bf16_f32 v32, v32, v33
	v_pk_mul_f32 v[38:39], v[200:201], v[38:39]
	s_nop 0
	v_cvt_pk_bf16_f32 v33, v38, v39
	global_store_dwordx2 v[44:45], v[32:33], off offset:16
	v_pk_mul_f32 v[32:33], v[62:63], v[42:43] op_sel_hi:[1,0]
	v_pk_mul_f32 v[32:33], v[202:203], v[32:33]
	v_pk_mul_f32 v[38:39], v[204:205], v[52:53]
	v_cvt_pk_bf16_f32 v32, v32, v33
	v_cvt_pk_bf16_f32 v33, v38, v39
	global_store_dwordx2 v[44:45], v[32:33], off offset:32
	v_pk_mul_f32 v[32:33], v[72:73], v[42:43] op_sel_hi:[1,0]
	v_pk_mul_f32 v[52:53], v[78:79], v[42:43] op_sel_hi:[1,0]
	v_pk_mul_f32 v[32:33], v[206:207], v[32:33]
	v_pk_mul_f32 v[38:39], v[208:209], v[52:53]
	v_cvt_pk_bf16_f32 v32, v32, v33
	v_cvt_pk_bf16_f32 v33, v38, v39
	global_store_dwordx2 v[44:45], v[32:33], off offset:48
	v_pk_mul_f32 v[32:33], v[68:69], v[42:43] op_sel_hi:[1,0]
	v_pk_mul_f32 v[52:53], v[76:77], v[42:43] op_sel_hi:[1,0]
	v_pk_mul_f32 v[32:33], v[210:211], v[32:33]
	v_pk_mul_f32 v[38:39], v[212:213], v[52:53]
	v_cvt_pk_bf16_f32 v32, v32, v33
	v_cvt_pk_bf16_f32 v33, v38, v39
	global_store_dwordx2 v[44:45], v[32:33], off offset:64
	v_pk_mul_f32 v[32:33], v[66:67], v[42:43] op_sel_hi:[1,0]
	v_pk_mul_f32 v[52:53], v[74:75], v[42:43] op_sel_hi:[1,0]
	v_pk_mul_f32 v[32:33], v[214:215], v[32:33]
	v_pk_mul_f32 v[38:39], v[216:217], v[52:53]
	v_cvt_pk_bf16_f32 v32, v32, v33
	v_cvt_pk_bf16_f32 v33, v38, v39
	global_store_dwordx2 v[44:45], v[32:33], off offset:80
	v_pk_mul_f32 v[32:33], v[64:65], v[42:43] op_sel_hi:[1,0]
	v_pk_mul_f32 v[52:53], v[70:71], v[42:43] op_sel_hi:[1,0]
	v_pk_mul_f32 v[32:33], v[32:33], v[218:219]
	v_pk_mul_f32 v[38:39], v[52:53], v[220:221]
	v_cvt_pk_bf16_f32 v32, v32, v33
	v_cvt_pk_bf16_f32 v33, v38, v39
	global_store_dwordx2 v[44:45], v[32:33], off offset:96
	v_pk_mul_f32 v[32:33], v[54:55], v[42:43] op_sel_hi:[1,0]
	v_pk_mul_f32 v[52:53], v[60:61], v[42:43] op_sel_hi:[1,0]
	v_pk_mul_f32 v[32:33], v[32:33], v[222:223]
	v_pk_mul_f32 v[38:39], v[52:53], v[224:225]
	v_cvt_pk_bf16_f32 v32, v32, v33
	v_cvt_pk_bf16_f32 v33, v38, v39
	global_store_dwordx2 v[44:45], v[32:33], off offset:112
	v_pk_mul_f32 v[32:33], v[50:51], v[42:43] op_sel_hi:[1,0]
	v_pk_mul_f32 v[50:51], v[58:59], v[42:43] op_sel_hi:[1,0]
	v_pk_mul_f32 v[32:33], v[32:33], v[226:227]
	v_pk_mul_f32 v[38:39], v[50:51], v[228:229]
	v_cvt_pk_bf16_f32 v32, v32, v33
	v_cvt_pk_bf16_f32 v33, v38, v39
	global_store_dwordx2 v[44:45], v[32:33], off offset:128
	v_pk_mul_f32 v[32:33], v[48:49], v[42:43] op_sel_hi:[1,0]
	v_pk_mul_f32 v[48:49], v[56:57], v[42:43] op_sel_hi:[1,0]
	v_pk_mul_f32 v[32:33], v[32:33], v[230:231]
	v_pk_mul_f32 v[38:39], v[48:49], v[232:233]
	v_cvt_pk_bf16_f32 v32, v32, v33
	v_cvt_pk_bf16_f32 v33, v38, v39
	global_store_dwordx2 v[44:45], v[32:33], off offset:144
	v_pk_mul_f32 v[32:33], v[132:133], v[42:43] op_sel_hi:[1,0]
	v_pk_mul_f32 v[32:33], v[32:33], v[234:235]
	v_pk_mul_f32 v[38:39], v[46:47], v[236:237]
	v_cvt_pk_bf16_f32 v32, v32, v33
	v_cvt_pk_bf16_f32 v33, v38, v39
	global_store_dwordx2 v[44:45], v[32:33], off offset:160
	v_pk_mul_f32 v[32:33], v[36:37], v[42:43] op_sel_hi:[1,0]
	v_pk_mul_f32 v[30:31], v[30:31], v[240:241]
	v_pk_mul_f32 v[32:33], v[32:33], v[238:239]
	s_nop 0
	v_cvt_pk_bf16_f32 v32, v32, v33
	v_cvt_pk_bf16_f32 v33, v30, v31
	global_store_dwordx2 v[44:45], v[32:33], off offset:176
	v_pk_mul_f32 v[30:31], v[34:35], v[242:243]
	v_pk_mul_f32 v[26:27], v[26:27], v[244:245]
	v_cvt_pk_bf16_f32 v30, v30, v31
	v_cvt_pk_bf16_f32 v31, v26, v27
	global_store_dwordx2 v[44:45], v[30:31], off offset:192
	v_pk_mul_f32 v[26:27], v[28:29], v[42:43] op_sel_hi:[1,0]
	v_pk_mul_f32 v[24:25], v[24:25], v[248:249]
	v_pk_mul_f32 v[26:27], v[26:27], v[246:247]
	s_nop 0
	v_cvt_pk_bf16_f32 v26, v26, v27
	v_cvt_pk_bf16_f32 v27, v24, v25
	global_store_dwordx2 v[44:45], v[26:27], off offset:208
	v_pk_mul_f32 v[20:21], v[20:21], v[184:185]
	v_pk_mul_f32 v[22:23], v[22:23], v[186:187]
	v_cvt_pk_bf16_f32 v20, v20, v21
	v_cvt_pk_bf16_f32 v21, v22, v23
	global_store_dwordx2 v[44:45], v[20:21], off offset:224
	v_pk_mul_f32 v[16:17], v[16:17], v[128:129]
	v_pk_mul_f32 v[18:19], v[18:19], v[130:131]
	v_cvt_pk_bf16_f32 v16, v16, v17
	v_cvt_pk_bf16_f32 v17, v18, v19
	global_store_dwordx2 v[44:45], v[16:17], off offset:240
	s_branch .LBB0_427

.LBB0_594:
	s_lshr_b32 s0, s28, 5
	s_mulk_i32 s0, 0x1800
	s_ashr_i32 s1, s0, 31
	s_lshl_b64 s[0:1], s[0:1], 2
	s_add_u32 s0, s52, s0
	s_addc_u32 s1, s53, s1
	v_lshl_add_u32 v150, s28, 8, v154
	v_lshl_or_b32 v152, s26, 8, v156
	v_lshlrev_b32_e32 v144, 2, v152
	s_add_u32 s26, s0, 0x2000
	s_addc_u32 s27, s1, 0
	s_add_u32 s28, s0, 0x4000
	s_addc_u32 s29, s1, 0
	global_load_dwordx4 v[190:193], v144, s[26:27]
	global_load_dwordx4 v[194:197], v144, s[26:27] offset:16
	global_load_dwordx4 v[198:201], v144, s[26:27] offset:512
	global_load_dwordx4 v[202:205], v144, s[26:27] offset:528
	global_load_dwordx4 v[206:209], v144, s[82:83]
	global_load_dwordx4 v[210:213], v144, s[82:83] offset:16
	global_load_dwordx4 v[214:217], v144, s[82:83] offset:512
	global_load_dwordx4 v[218:221], v144, s[82:83] offset:528
	global_load_dwordx4 v[222:225], v144, s[28:29]
	global_load_dwordx4 v[226:229], v144, s[28:29] offset:16
	global_load_dwordx4 v[230:233], v144, s[28:29] offset:512
	global_load_dwordx4 v[234:237], v144, s[28:29] offset:528
	v_lshl_add_u32 v145, v150, 12, v144
	v_lshrrev_b32_e32 v146, 1, v145
	v_lshlrev_b32_e32 v147, 2, v150
	v_xor_b32_e32 v148, 16, v160
	v_lshlrev_b32_e32 v148, 2, v148
	v_xor_b32_e32 v149, 32, v160
	v_lshlrev_b32_e32 v149, 2, v149
	global_load_dwordx4 v[238:241], v145, s[40:41]
	global_load_dwordx4 v[242:245], v145, s[40:41] offset:16
	global_load_dwordx4 v[246:249], v145, s[40:41] offset:512
	global_load_dwordx4 v[162:165], v145, s[40:41] offset:528
	s_add_u32 s0, s40, 0x10000
	s_addc_u32 s1, s41, 0
	global_load_dwordx4 v[166:169], v145, s[0:1]
	global_load_dwordx4 v[170:173], v145, s[0:1] offset:16
	global_load_dwordx4 v[174:177], v145, s[0:1] offset:512
	global_load_dwordx4 v[178:181], v145, s[0:1] offset:528
	s_waitcnt vmcnt(4)
	v_pk_add_f32 v[222:223], v[222:223], 1.0 op_sel_hi:[1,0]
	v_pk_add_f32 v[224:225], v[224:225], 1.0 op_sel_hi:[1,0]
	v_pk_add_f32 v[226:227], v[226:227], 1.0 op_sel_hi:[1,0]
	v_pk_add_f32 v[228:229], v[228:229], 1.0 op_sel_hi:[1,0]
	v_pk_add_f32 v[230:231], v[230:231], 1.0 op_sel_hi:[1,0]
	v_pk_add_f32 v[232:233], v[232:233], 1.0 op_sel_hi:[1,0]
	v_pk_add_f32 v[234:235], v[234:235], 1.0 op_sel_hi:[1,0]
	v_pk_add_f32 v[236:237], v[236:237], 1.0 op_sel_hi:[1,0]
	s_add_u32 s26, s72, 0x0
	s_addc_u32 s27, s73, 0
	s_add_u32 s28, s10, 0x0
	s_addc_u32 s29, s11, 0
	v_pk_fma_f32 v[124:125], v[124:125], v[190:191], v[238:239]
	v_pk_fma_f32 v[126:127], v[126:127], v[192:193], v[240:241]
	global_store_dwordx4 v145, v[124:127], s[26:27]
	v_mul_f32_e32 v161, v125, v125
	v_mul_f32_e32 v186, v127, v127
	v_fmac_f32_e32 v161, v124, v124
	v_fmac_f32_e32 v186, v126, v126
	v_add_f32_e32 v187, v161, v186
	v_pk_mul_f32 v[238:239], v[206:207], v[124:125]
	v_pk_mul_f32 v[240:241], v[208:209], v[126:127]
	v_pk_mul_f32 v[238:239], v[222:223], v[238:239]
	v_pk_mul_f32 v[240:241], v[224:225], v[240:241]
	v_cvt_pk_bf16_f32 v182, v238, v239
	v_cvt_pk_bf16_f32 v183, v240, v241
	v_pk_fma_f32 v[120:121], v[120:121], v[194:195], v[242:243]
	v_pk_fma_f32 v[122:123], v[122:123], v[196:197], v[244:245]
	global_store_dwordx4 v145, v[120:123], s[26:27] offset:16
	v_mul_f32_e32 v161, v121, v121
	v_mul_f32_e32 v186, v123, v123
	v_fmac_f32_e32 v161, v120, v120
	v_fmac_f32_e32 v186, v122, v122
	v_add_f32_e32 v161, v161, v186
	v_add_f32_e32 v187, v187, v161
	v_pk_mul_f32 v[242:243], v[210:211], v[120:121]
	v_pk_mul_f32 v[244:245], v[212:213], v[122:123]
	v_pk_mul_f32 v[242:243], v[226:227], v[242:243]
	v_pk_mul_f32 v[244:245], v[228:229], v[244:245]
	v_cvt_pk_bf16_f32 v184, v242, v243
	v_cvt_pk_bf16_f32 v185, v244, v245
	global_store_dwordx4 v146, v[182:185], s[28:29]
	v_pk_fma_f32 v[116:117], v[116:117], v[198:199], v[246:247]
	v_pk_fma_f32 v[118:119], v[118:119], v[200:201], v[248:249]
	global_store_dwordx4 v145, v[116:119], s[26:27] offset:512
	v_mul_f32_e32 v161, v117, v117
	v_mul_f32_e32 v186, v119, v119
	v_fmac_f32_e32 v161, v116, v116
	v_fmac_f32_e32 v186, v118, v118
	v_add_f32_e32 v161, v161, v186
	v_add_f32_e32 v187, v187, v161
	v_pk_mul_f32 v[246:247], v[214:215], v[116:117]
	v_pk_mul_f32 v[248:249], v[216:217], v[118:119]
	v_pk_mul_f32 v[246:247], v[230:231], v[246:247]
	v_pk_mul_f32 v[248:249], v[232:233], v[248:249]
	v_cvt_pk_bf16_f32 v150, v246, v247
	v_cvt_pk_bf16_f32 v151, v248, v249
	v_pk_fma_f32 v[112:113], v[112:113], v[202:203], v[162:163]
	v_pk_fma_f32 v[114:115], v[114:115], v[204:205], v[164:165]
	global_store_dwordx4 v145, v[112:115], s[26:27] offset:528
	v_mul_f32_e32 v161, v113, v113
	v_mul_f32_e32 v186, v115, v115
	v_fmac_f32_e32 v161, v112, v112
	v_fmac_f32_e32 v186, v114, v114
	v_add_f32_e32 v161, v161, v186
	v_add_f32_e32 v187, v187, v161
	v_pk_mul_f32 v[162:163], v[218:219], v[112:113]
	v_pk_mul_f32 v[164:165], v[220:221], v[114:115]
	v_pk_mul_f32 v[162:163], v[234:235], v[162:163]
	v_pk_mul_f32 v[164:165], v[236:237], v[164:165]
	v_cvt_pk_bf16_f32 v152, v162, v163
	v_cvt_pk_bf16_f32 v153, v164, v165
	global_store_dwordx4 v146, v[150:153], s[28:29] offset:256
	ds_bpermute_b32 v186, v148, v187
	s_add_u32 s26, s12, 0x0
	s_addc_u32 s27, s13, 0
	s_waitcnt lgkmcnt(0)
	v_add_f32_e32 v187, v187, v186
	ds_bpermute_b32 v186, v149, v187
	s_waitcnt lgkmcnt(0)
	v_add_f32_e32 v187, v187, v186
	s_and_saveexec_b64 s[28:29], s[2:3]
	global_atomic_add_f32 v147, v187, s[26:27]
	s_mov_b64 exec, s[28:29]
	s_add_u32 s0, s40, 0x20000
	s_addc_u32 s1, s41, 0
	global_load_dwordx4 v[238:241], v145, s[0:1]
	global_load_dwordx4 v[242:245], v145, s[0:1] offset:16
	global_load_dwordx4 v[246:249], v145, s[0:1] offset:512
	global_load_dwordx4 v[162:165], v145, s[0:1] offset:528
	s_waitcnt vmcnt(11)
	s_add_u32 s26, s72, 0x10000
	s_addc_u32 s27, s73, 0
	s_add_u32 s28, s10, 0x8000
	s_addc_u32 s29, s11, 0
	v_pk_fma_f32 v[108:109], v[108:109], v[190:191], v[166:167]
	v_pk_fma_f32 v[110:111], v[110:111], v[192:193], v[168:169]
	global_store_dwordx4 v145, v[108:111], s[26:27]
	v_mul_f32_e32 v161, v109, v109
	v_mul_f32_e32 v186, v111, v111
	v_fmac_f32_e32 v161, v108, v108
	v_fmac_f32_e32 v186, v110, v110
	v_add_f32_e32 v187, v161, v186
	v_pk_mul_f32 v[166:167], v[206:207], v[108:109]
	v_pk_mul_f32 v[168:169], v[208:209], v[110:111]
	v_pk_mul_f32 v[166:167], v[222:223], v[166:167]
	v_pk_mul_f32 v[168:169], v[224:225], v[168:169]
	v_cvt_pk_bf16_f32 v182, v166, v167
	v_cvt_pk_bf16_f32 v183, v168, v169
	v_pk_fma_f32 v[104:105], v[104:105], v[194:195], v[170:171]
	v_pk_fma_f32 v[106:107], v[106:107], v[196:197], v[172:173]
	global_store_dwordx4 v145, v[104:107], s[26:27] offset:16
	v_mul_f32_e32 v161, v105, v105
	v_mul_f32_e32 v186, v107, v107
	v_fmac_f32_e32 v161, v104, v104
	v_fmac_f32_e32 v186, v106, v106
	v_add_f32_e32 v161, v161, v186
	v_add_f32_e32 v187, v187, v161
	v_pk_mul_f32 v[170:171], v[210:211], v[104:105]
	v_pk_mul_f32 v[172:173], v[212:213], v[106:107]
	v_pk_mul_f32 v[170:171], v[226:227], v[170:171]
	v_pk_mul_f32 v[172:173], v[228:229], v[172:173]
	v_cvt_pk_bf16_f32 v184, v170, v171
	v_cvt_pk_bf16_f32 v185, v172, v173
	global_store_dwordx4 v146, v[182:185], s[28:29]
	v_pk_fma_f32 v[100:101], v[100:101], v[198:199], v[174:175]
	v_pk_fma_f32 v[102:103], v[102:103], v[200:201], v[176:177]
	global_store_dwordx4 v145, v[100:103], s[26:27] offset:512
	v_mul_f32_e32 v161, v101, v101
	v_mul_f32_e32 v186, v103, v103
	v_fmac_f32_e32 v161, v100, v100
	v_fmac_f32_e32 v186, v102, v102
	v_add_f32_e32 v161, v161, v186
	v_add_f32_e32 v187, v187, v161
	v_pk_mul_f32 v[174:175], v[214:215], v[100:101]
	v_pk_mul_f32 v[176:177], v[216:217], v[102:103]
	v_pk_mul_f32 v[174:175], v[230:231], v[174:175]
	v_pk_mul_f32 v[176:177], v[232:233], v[176:177]
	v_cvt_pk_bf16_f32 v150, v174, v175
	v_cvt_pk_bf16_f32 v151, v176, v177
	v_pk_fma_f32 v[96:97], v[96:97], v[202:203], v[178:179]
	v_pk_fma_f32 v[98:99], v[98:99], v[204:205], v[180:181]
	global_store_dwordx4 v145, v[96:99], s[26:27] offset:528
	v_mul_f32_e32 v161, v97, v97
	v_mul_f32_e32 v186, v99, v99
	v_fmac_f32_e32 v161, v96, v96
	v_fmac_f32_e32 v186, v98, v98
	v_add_f32_e32 v161, v161, v186
	v_add_f32_e32 v187, v187, v161
	v_pk_mul_f32 v[178:179], v[218:219], v[96:97]
	v_pk_mul_f32 v[180:181], v[220:221], v[98:99]
	v_pk_mul_f32 v[178:179], v[234:235], v[178:179]
	v_pk_mul_f32 v[180:181], v[236:237], v[180:181]
	v_cvt_pk_bf16_f32 v152, v178, v179
	v_cvt_pk_bf16_f32 v153, v180, v181
	global_store_dwordx4 v146, v[150:153], s[28:29] offset:256
	ds_bpermute_b32 v186, v148, v187
	s_add_u32 s26, s12, 0x40
	s_addc_u32 s27, s13, 0
	s_waitcnt lgkmcnt(0)
	v_add_f32_e32 v187, v187, v186
	ds_bpermute_b32 v186, v149, v187
	s_waitcnt lgkmcnt(0)
	v_add_f32_e32 v187, v187, v186
	s_and_saveexec_b64 s[28:29], s[2:3]
	global_atomic_add_f32 v147, v187, s[26:27]
	s_mov_b64 exec, s[28:29]
	s_add_u32 s0, s40, 0x30000
	s_addc_u32 s1, s41, 0
	global_load_dwordx4 v[166:169], v145, s[0:1]
	global_load_dwordx4 v[170:173], v145, s[0:1] offset:16
	global_load_dwordx4 v[174:177], v145, s[0:1] offset:512
	global_load_dwordx4 v[178:181], v145, s[0:1] offset:528
	s_waitcnt vmcnt(11)
	s_add_u32 s26, s72, 0x20000
	s_addc_u32 s27, s73, 0
	s_add_u32 s28, s10, 0x10000
	s_addc_u32 s29, s11, 0
	v_pk_fma_f32 v[92:93], v[92:93], v[190:191], v[238:239]
	v_pk_fma_f32 v[94:95], v[94:95], v[192:193], v[240:241]
	global_store_dwordx4 v145, v[92:95], s[26:27]
	v_mul_f32_e32 v161, v93, v93
	v_mul_f32_e32 v186, v95, v95
	v_fmac_f32_e32 v161, v92, v92
	v_fmac_f32_e32 v186, v94, v94
	v_add_f32_e32 v187, v161, v186
	v_pk_mul_f32 v[238:239], v[206:207], v[92:93]
	v_pk_mul_f32 v[240:241], v[208:209], v[94:95]
	v_pk_mul_f32 v[238:239], v[222:223], v[238:239]
	v_pk_mul_f32 v[240:241], v[224:225], v[240:241]
	v_cvt_pk_bf16_f32 v182, v238, v239
	v_cvt_pk_bf16_f32 v183, v240, v241
	v_pk_fma_f32 v[88:89], v[88:89], v[194:195], v[242:243]
	v_pk_fma_f32 v[90:91], v[90:91], v[196:197], v[244:245]
	global_store_dwordx4 v145, v[88:91], s[26:27] offset:16
	v_mul_f32_e32 v161, v89, v89
	v_mul_f32_e32 v186, v91, v91
	v_fmac_f32_e32 v161, v88, v88
	v_fmac_f32_e32 v186, v90, v90
	v_add_f32_e32 v161, v161, v186
	v_add_f32_e32 v187, v187, v161
	v_pk_mul_f32 v[242:243], v[210:211], v[88:89]
	v_pk_mul_f32 v[244:245], v[212:213], v[90:91]
	v_pk_mul_f32 v[242:243], v[226:227], v[242:243]
	v_pk_mul_f32 v[244:245], v[228:229], v[244:245]
	v_cvt_pk_bf16_f32 v184, v242, v243
	v_cvt_pk_bf16_f32 v185, v244, v245
	global_store_dwordx4 v146, v[182:185], s[28:29]
	v_pk_fma_f32 v[84:85], v[84:85], v[198:199], v[246:247]
	v_pk_fma_f32 v[86:87], v[86:87], v[200:201], v[248:249]
	global_store_dwordx4 v145, v[84:87], s[26:27] offset:512
	v_mul_f32_e32 v161, v85, v85
	v_mul_f32_e32 v186, v87, v87
	v_fmac_f32_e32 v161, v84, v84
	v_fmac_f32_e32 v186, v86, v86
	v_add_f32_e32 v161, v161, v186
	v_add_f32_e32 v187, v187, v161
	v_pk_mul_f32 v[246:247], v[214:215], v[84:85]
	v_pk_mul_f32 v[248:249], v[216:217], v[86:87]
	v_pk_mul_f32 v[246:247], v[230:231], v[246:247]
	v_pk_mul_f32 v[248:249], v[232:233], v[248:249]
	v_cvt_pk_bf16_f32 v150, v246, v247
	v_cvt_pk_bf16_f32 v151, v248, v249
	v_pk_fma_f32 v[80:81], v[80:81], v[202:203], v[162:163]
	v_pk_fma_f32 v[82:83], v[82:83], v[204:205], v[164:165]
	global_store_dwordx4 v145, v[80:83], s[26:27] offset:528
	v_mul_f32_e32 v161, v81, v81
	v_mul_f32_e32 v186, v83, v83
	v_fmac_f32_e32 v161, v80, v80
	v_fmac_f32_e32 v186, v82, v82
	v_add_f32_e32 v161, v161, v186
	v_add_f32_e32 v187, v187, v161
	v_pk_mul_f32 v[162:163], v[218:219], v[80:81]
	v_pk_mul_f32 v[164:165], v[220:221], v[82:83]
	v_pk_mul_f32 v[162:163], v[234:235], v[162:163]
	v_pk_mul_f32 v[164:165], v[236:237], v[164:165]
	v_cvt_pk_bf16_f32 v152, v162, v163
	v_cvt_pk_bf16_f32 v153, v164, v165
	global_store_dwordx4 v146, v[150:153], s[28:29] offset:256
	ds_bpermute_b32 v186, v148, v187
	s_add_u32 s26, s12, 0x80
	s_addc_u32 s27, s13, 0
	s_waitcnt lgkmcnt(0)
	v_add_f32_e32 v187, v187, v186
	ds_bpermute_b32 v186, v149, v187
	s_waitcnt lgkmcnt(0)
	v_add_f32_e32 v187, v187, v186
	s_and_saveexec_b64 s[28:29], s[2:3]
	global_atomic_add_f32 v147, v187, s[26:27]
	s_mov_b64 exec, s[28:29]
	s_add_u32 s0, s40, 0x80000
	s_addc_u32 s1, s41, 0
	global_load_dwordx4 v[238:241], v145, s[0:1]
	global_load_dwordx4 v[242:245], v145, s[0:1] offset:16
	global_load_dwordx4 v[246:249], v145, s[0:1] offset:512
	global_load_dwordx4 v[162:165], v145, s[0:1] offset:528
	s_waitcnt vmcnt(11)
	s_add_u32 s26, s72, 0x30000
	s_addc_u32 s27, s73, 0
	s_add_u32 s28, s10, 0x18000
	s_addc_u32 s29, s11, 0
	v_pk_fma_f32 v[76:77], v[76:77], v[190:191], v[166:167]
	v_pk_fma_f32 v[78:79], v[78:79], v[192:193], v[168:169]
	global_store_dwordx4 v145, v[76:79], s[26:27]
	v_mul_f32_e32 v161, v77, v77
	v_mul_f32_e32 v186, v79, v79
	v_fmac_f32_e32 v161, v76, v76
	v_fmac_f32_e32 v186, v78, v78
	v_add_f32_e32 v187, v161, v186
	v_pk_mul_f32 v[166:167], v[206:207], v[76:77]
	v_pk_mul_f32 v[168:169], v[208:209], v[78:79]
	v_pk_mul_f32 v[166:167], v[222:223], v[166:167]
	v_pk_mul_f32 v[168:169], v[224:225], v[168:169]
	v_cvt_pk_bf16_f32 v182, v166, v167
	v_cvt_pk_bf16_f32 v183, v168, v169
	v_pk_fma_f32 v[72:73], v[72:73], v[194:195], v[170:171]
	v_pk_fma_f32 v[74:75], v[74:75], v[196:197], v[172:173]
	global_store_dwordx4 v145, v[72:75], s[26:27] offset:16
	v_mul_f32_e32 v161, v73, v73
	v_mul_f32_e32 v186, v75, v75
	v_fmac_f32_e32 v161, v72, v72
	v_fmac_f32_e32 v186, v74, v74
	v_add_f32_e32 v161, v161, v186
	v_add_f32_e32 v187, v187, v161
	v_pk_mul_f32 v[170:171], v[210:211], v[72:73]
	v_pk_mul_f32 v[172:173], v[212:213], v[74:75]
	v_pk_mul_f32 v[170:171], v[226:227], v[170:171]
	v_pk_mul_f32 v[172:173], v[228:229], v[172:173]
	v_cvt_pk_bf16_f32 v184, v170, v171
	v_cvt_pk_bf16_f32 v185, v172, v173
	global_store_dwordx4 v146, v[182:185], s[28:29]
	v_pk_fma_f32 v[68:69], v[68:69], v[198:199], v[174:175]
	v_pk_fma_f32 v[70:71], v[70:71], v[200:201], v[176:177]
	global_store_dwordx4 v145, v[68:71], s[26:27] offset:512
	v_mul_f32_e32 v161, v69, v69
	v_mul_f32_e32 v186, v71, v71
	v_fmac_f32_e32 v161, v68, v68
	v_fmac_f32_e32 v186, v70, v70
	v_add_f32_e32 v161, v161, v186
	v_add_f32_e32 v187, v187, v161
	v_pk_mul_f32 v[174:175], v[214:215], v[68:69]
	v_pk_mul_f32 v[176:177], v[216:217], v[70:71]
	v_pk_mul_f32 v[174:175], v[230:231], v[174:175]
	v_pk_mul_f32 v[176:177], v[232:233], v[176:177]
	v_cvt_pk_bf16_f32 v150, v174, v175
	v_cvt_pk_bf16_f32 v151, v176, v177
	v_pk_fma_f32 v[64:65], v[64:65], v[202:203], v[178:179]
	v_pk_fma_f32 v[66:67], v[66:67], v[204:205], v[180:181]
	global_store_dwordx4 v145, v[64:67], s[26:27] offset:528
	v_mul_f32_e32 v161, v65, v65
	v_mul_f32_e32 v186, v67, v67
	v_fmac_f32_e32 v161, v64, v64
	v_fmac_f32_e32 v186, v66, v66
	v_add_f32_e32 v161, v161, v186
	v_add_f32_e32 v187, v187, v161
	v_pk_mul_f32 v[178:179], v[218:219], v[64:65]
	v_pk_mul_f32 v[180:181], v[220:221], v[66:67]
	v_pk_mul_f32 v[178:179], v[234:235], v[178:179]
	v_pk_mul_f32 v[180:181], v[236:237], v[180:181]
	v_cvt_pk_bf16_f32 v152, v178, v179
	v_cvt_pk_bf16_f32 v153, v180, v181
	global_store_dwordx4 v146, v[150:153], s[28:29] offset:256
	ds_bpermute_b32 v186, v148, v187
	s_add_u32 s26, s12, 0xc0
	s_addc_u32 s27, s13, 0
	s_waitcnt lgkmcnt(0)
	v_add_f32_e32 v187, v187, v186
	ds_bpermute_b32 v186, v149, v187
	s_waitcnt lgkmcnt(0)
	v_add_f32_e32 v187, v187, v186
	s_and_saveexec_b64 s[28:29], s[2:3]
	global_atomic_add_f32 v147, v187, s[26:27]
	s_mov_b64 exec, s[28:29]
	s_add_u32 s0, s40, 0x90000
	s_addc_u32 s1, s41, 0
	global_load_dwordx4 v[166:169], v145, s[0:1]
	global_load_dwordx4 v[170:173], v145, s[0:1] offset:16
	global_load_dwordx4 v[174:177], v145, s[0:1] offset:512
	global_load_dwordx4 v[178:181], v145, s[0:1] offset:528
	s_waitcnt vmcnt(11)
	s_add_u32 s26, s72, 0x80000
	s_addc_u32 s27, s73, 0
	s_add_u32 s28, s10, 0x40000
	s_addc_u32 s29, s11, 0
	v_pk_fma_f32 v[60:61], v[60:61], v[190:191], v[238:239]
	v_pk_fma_f32 v[62:63], v[62:63], v[192:193], v[240:241]
	global_store_dwordx4 v145, v[60:63], s[26:27]
	v_mul_f32_e32 v161, v61, v61
	v_mul_f32_e32 v186, v63, v63
	v_fmac_f32_e32 v161, v60, v60
	v_fmac_f32_e32 v186, v62, v62
	v_add_f32_e32 v187, v161, v186
	v_pk_mul_f32 v[238:239], v[206:207], v[60:61]
	v_pk_mul_f32 v[240:241], v[208:209], v[62:63]
	v_pk_mul_f32 v[238:239], v[222:223], v[238:239]
	v_pk_mul_f32 v[240:241], v[224:225], v[240:241]
	v_cvt_pk_bf16_f32 v182, v238, v239
	v_cvt_pk_bf16_f32 v183, v240, v241
	v_pk_fma_f32 v[56:57], v[56:57], v[194:195], v[242:243]
	v_pk_fma_f32 v[58:59], v[58:59], v[196:197], v[244:245]
	global_store_dwordx4 v145, v[56:59], s[26:27] offset:16
	v_mul_f32_e32 v161, v57, v57
	v_mul_f32_e32 v186, v59, v59
	v_fmac_f32_e32 v161, v56, v56
	v_fmac_f32_e32 v186, v58, v58
	v_add_f32_e32 v161, v161, v186
	v_add_f32_e32 v187, v187, v161
	v_pk_mul_f32 v[242:243], v[210:211], v[56:57]
	v_pk_mul_f32 v[244:245], v[212:213], v[58:59]
	v_pk_mul_f32 v[242:243], v[226:227], v[242:243]
	v_pk_mul_f32 v[244:245], v[228:229], v[244:245]
	v_cvt_pk_bf16_f32 v184, v242, v243
	v_cvt_pk_bf16_f32 v185, v244, v245
	global_store_dwordx4 v146, v[182:185], s[28:29]
	v_pk_fma_f32 v[52:53], v[52:53], v[198:199], v[246:247]
	v_pk_fma_f32 v[54:55], v[54:55], v[200:201], v[248:249]
	global_store_dwordx4 v145, v[52:55], s[26:27] offset:512
	v_mul_f32_e32 v161, v53, v53
	v_mul_f32_e32 v186, v55, v55
	v_fmac_f32_e32 v161, v52, v52
	v_fmac_f32_e32 v186, v54, v54
	v_add_f32_e32 v161, v161, v186
	v_add_f32_e32 v187, v187, v161
	v_pk_mul_f32 v[246:247], v[214:215], v[52:53]
	v_pk_mul_f32 v[248:249], v[216:217], v[54:55]
	v_pk_mul_f32 v[246:247], v[230:231], v[246:247]
	v_pk_mul_f32 v[248:249], v[232:233], v[248:249]
	v_cvt_pk_bf16_f32 v150, v246, v247
	v_cvt_pk_bf16_f32 v151, v248, v249
	v_pk_fma_f32 v[48:49], v[48:49], v[202:203], v[162:163]
	v_pk_fma_f32 v[50:51], v[50:51], v[204:205], v[164:165]
	global_store_dwordx4 v145, v[48:51], s[26:27] offset:528
	v_mul_f32_e32 v161, v49, v49
	v_mul_f32_e32 v186, v51, v51
	v_fmac_f32_e32 v161, v48, v48
	v_fmac_f32_e32 v186, v50, v50
	v_add_f32_e32 v161, v161, v186
	v_add_f32_e32 v187, v187, v161
	v_pk_mul_f32 v[162:163], v[218:219], v[48:49]
	v_pk_mul_f32 v[164:165], v[220:221], v[50:51]
	v_pk_mul_f32 v[162:163], v[234:235], v[162:163]
	v_pk_mul_f32 v[164:165], v[236:237], v[164:165]
	v_cvt_pk_bf16_f32 v152, v162, v163
	v_cvt_pk_bf16_f32 v153, v164, v165
	global_store_dwordx4 v146, v[150:153], s[28:29] offset:256
	ds_bpermute_b32 v186, v148, v187
	s_add_u32 s26, s12, 0x200
	s_addc_u32 s27, s13, 0
	s_waitcnt lgkmcnt(0)
	v_add_f32_e32 v187, v187, v186
	ds_bpermute_b32 v186, v149, v187
	s_waitcnt lgkmcnt(0)
	v_add_f32_e32 v187, v187, v186
	s_and_saveexec_b64 s[28:29], s[2:3]
	global_atomic_add_f32 v147, v187, s[26:27]
	s_mov_b64 exec, s[28:29]
	s_add_u32 s0, s40, 0xa0000
	s_addc_u32 s1, s41, 0
	global_load_dwordx4 v[238:241], v145, s[0:1]
	global_load_dwordx4 v[242:245], v145, s[0:1] offset:16
	global_load_dwordx4 v[246:249], v145, s[0:1] offset:512
	global_load_dwordx4 v[162:165], v145, s[0:1] offset:528
	s_waitcnt vmcnt(11)
	s_add_u32 s26, s72, 0x90000
	s_addc_u32 s27, s73, 0
	s_add_u32 s28, s10, 0x48000
	s_addc_u32 s29, s11, 0
	v_pk_fma_f32 v[44:45], v[44:45], v[190:191], v[166:167]
	v_pk_fma_f32 v[46:47], v[46:47], v[192:193], v[168:169]
	global_store_dwordx4 v145, v[44:47], s[26:27]
	v_mul_f32_e32 v161, v45, v45
	v_mul_f32_e32 v186, v47, v47
	v_fmac_f32_e32 v161, v44, v44
	v_fmac_f32_e32 v186, v46, v46
	v_add_f32_e32 v187, v161, v186
	v_pk_mul_f32 v[166:167], v[206:207], v[44:45]
	v_pk_mul_f32 v[168:169], v[208:209], v[46:47]
	v_pk_mul_f32 v[166:167], v[222:223], v[166:167]
	v_pk_mul_f32 v[168:169], v[224:225], v[168:169]
	v_cvt_pk_bf16_f32 v182, v166, v167
	v_cvt_pk_bf16_f32 v183, v168, v169
	v_pk_fma_f32 v[40:41], v[40:41], v[194:195], v[170:171]
	v_pk_fma_f32 v[42:43], v[42:43], v[196:197], v[172:173]
	global_store_dwordx4 v145, v[40:43], s[26:27] offset:16
	v_mul_f32_e32 v161, v41, v41
	v_mul_f32_e32 v186, v43, v43
	v_fmac_f32_e32 v161, v40, v40
	v_fmac_f32_e32 v186, v42, v42
	v_add_f32_e32 v161, v161, v186
	v_add_f32_e32 v187, v187, v161
	v_pk_mul_f32 v[170:171], v[210:211], v[40:41]
	v_pk_mul_f32 v[172:173], v[212:213], v[42:43]
	v_pk_mul_f32 v[170:171], v[226:227], v[170:171]
	v_pk_mul_f32 v[172:173], v[228:229], v[172:173]
	v_cvt_pk_bf16_f32 v184, v170, v171
	v_cvt_pk_bf16_f32 v185, v172, v173
	global_store_dwordx4 v146, v[182:185], s[28:29]
	v_pk_fma_f32 v[36:37], v[36:37], v[198:199], v[174:175]
	v_pk_fma_f32 v[38:39], v[38:39], v[200:201], v[176:177]
	global_store_dwordx4 v145, v[36:39], s[26:27] offset:512
	v_mul_f32_e32 v161, v37, v37
	v_mul_f32_e32 v186, v39, v39
	v_fmac_f32_e32 v161, v36, v36
	v_fmac_f32_e32 v186, v38, v38
	v_add_f32_e32 v161, v161, v186
	v_add_f32_e32 v187, v187, v161
	v_pk_mul_f32 v[174:175], v[214:215], v[36:37]
	v_pk_mul_f32 v[176:177], v[216:217], v[38:39]
	v_pk_mul_f32 v[174:175], v[230:231], v[174:175]
	v_pk_mul_f32 v[176:177], v[232:233], v[176:177]
	v_cvt_pk_bf16_f32 v150, v174, v175
	v_cvt_pk_bf16_f32 v151, v176, v177
	v_pk_fma_f32 v[32:33], v[32:33], v[202:203], v[178:179]
	v_pk_fma_f32 v[34:35], v[34:35], v[204:205], v[180:181]
	global_store_dwordx4 v145, v[32:35], s[26:27] offset:528
	v_mul_f32_e32 v161, v33, v33
	v_mul_f32_e32 v186, v35, v35
	v_fmac_f32_e32 v161, v32, v32
	v_fmac_f32_e32 v186, v34, v34
	v_add_f32_e32 v161, v161, v186
	v_add_f32_e32 v187, v187, v161
	v_pk_mul_f32 v[178:179], v[218:219], v[32:33]
	v_pk_mul_f32 v[180:181], v[220:221], v[34:35]
	v_pk_mul_f32 v[178:179], v[234:235], v[178:179]
	v_pk_mul_f32 v[180:181], v[236:237], v[180:181]
	v_cvt_pk_bf16_f32 v152, v178, v179
	v_cvt_pk_bf16_f32 v153, v180, v181
	global_store_dwordx4 v146, v[150:153], s[28:29] offset:256
	ds_bpermute_b32 v186, v148, v187
	s_add_u32 s26, s12, 0x240
	s_addc_u32 s27, s13, 0
	s_waitcnt lgkmcnt(0)
	v_add_f32_e32 v187, v187, v186
	ds_bpermute_b32 v186, v149, v187
	s_waitcnt lgkmcnt(0)
	v_add_f32_e32 v187, v187, v186
	s_and_saveexec_b64 s[28:29], s[2:3]
	global_atomic_add_f32 v147, v187, s[26:27]
	s_mov_b64 exec, s[28:29]
	s_add_u32 s0, s40, 0xb0000
	s_addc_u32 s1, s41, 0
	global_load_dwordx4 v[166:169], v145, s[0:1]
	global_load_dwordx4 v[170:173], v145, s[0:1] offset:16
	global_load_dwordx4 v[174:177], v145, s[0:1] offset:512
	global_load_dwordx4 v[178:181], v145, s[0:1] offset:528
	s_waitcnt vmcnt(11)
	s_add_u32 s26, s72, 0xa0000
	s_addc_u32 s27, s73, 0
	s_add_u32 s28, s10, 0x50000
	s_addc_u32 s29, s11, 0
	v_pk_fma_f32 v[28:29], v[28:29], v[190:191], v[238:239]
	v_pk_fma_f32 v[30:31], v[30:31], v[192:193], v[240:241]
	global_store_dwordx4 v145, v[28:31], s[26:27]
	v_mul_f32_e32 v161, v29, v29
	v_mul_f32_e32 v186, v31, v31
	v_fmac_f32_e32 v161, v28, v28
	v_fmac_f32_e32 v186, v30, v30
	v_add_f32_e32 v187, v161, v186
	v_pk_mul_f32 v[238:239], v[206:207], v[28:29]
	v_pk_mul_f32 v[240:241], v[208:209], v[30:31]
	v_pk_mul_f32 v[238:239], v[222:223], v[238:239]
	v_pk_mul_f32 v[240:241], v[224:225], v[240:241]
	v_cvt_pk_bf16_f32 v182, v238, v239
	v_cvt_pk_bf16_f32 v183, v240, v241
	v_pk_fma_f32 v[24:25], v[24:25], v[194:195], v[242:243]
	v_pk_fma_f32 v[26:27], v[26:27], v[196:197], v[244:245]
	global_store_dwordx4 v145, v[24:27], s[26:27] offset:16
	v_mul_f32_e32 v161, v25, v25
	v_mul_f32_e32 v186, v27, v27
	v_fmac_f32_e32 v161, v24, v24
	v_fmac_f32_e32 v186, v26, v26
	v_add_f32_e32 v161, v161, v186
	v_add_f32_e32 v187, v187, v161
	v_pk_mul_f32 v[242:243], v[210:211], v[24:25]
	v_pk_mul_f32 v[244:245], v[212:213], v[26:27]
	v_pk_mul_f32 v[242:243], v[226:227], v[242:243]
	v_pk_mul_f32 v[244:245], v[228:229], v[244:245]
	v_cvt_pk_bf16_f32 v184, v242, v243
	v_cvt_pk_bf16_f32 v185, v244, v245
	global_store_dwordx4 v146, v[182:185], s[28:29]
	v_pk_fma_f32 v[20:21], v[20:21], v[198:199], v[246:247]
	v_pk_fma_f32 v[22:23], v[22:23], v[200:201], v[248:249]
	global_store_dwordx4 v145, v[20:23], s[26:27] offset:512
	v_mul_f32_e32 v161, v21, v21
	v_mul_f32_e32 v186, v23, v23
	v_fmac_f32_e32 v161, v20, v20
	v_fmac_f32_e32 v186, v22, v22
	v_add_f32_e32 v161, v161, v186
	v_add_f32_e32 v187, v187, v161
	v_pk_mul_f32 v[246:247], v[214:215], v[20:21]
	v_pk_mul_f32 v[248:249], v[216:217], v[22:23]
	v_pk_mul_f32 v[246:247], v[230:231], v[246:247]
	v_pk_mul_f32 v[248:249], v[232:233], v[248:249]
	v_cvt_pk_bf16_f32 v150, v246, v247
	v_cvt_pk_bf16_f32 v151, v248, v249
	v_pk_fma_f32 v[16:17], v[16:17], v[202:203], v[162:163]
	v_pk_fma_f32 v[18:19], v[18:19], v[204:205], v[164:165]
	global_store_dwordx4 v145, v[16:19], s[26:27] offset:528
	v_mul_f32_e32 v161, v17, v17
	v_mul_f32_e32 v186, v19, v19
	v_fmac_f32_e32 v161, v16, v16
	v_fmac_f32_e32 v186, v18, v18
	v_add_f32_e32 v161, v161, v186
	v_add_f32_e32 v187, v187, v161
	v_pk_mul_f32 v[162:163], v[218:219], v[16:17]
	v_pk_mul_f32 v[164:165], v[220:221], v[18:19]
	v_pk_mul_f32 v[162:163], v[234:235], v[162:163]
	v_pk_mul_f32 v[164:165], v[236:237], v[164:165]
	v_cvt_pk_bf16_f32 v152, v162, v163
	v_cvt_pk_bf16_f32 v153, v164, v165
	global_store_dwordx4 v146, v[150:153], s[28:29] offset:256
	ds_bpermute_b32 v186, v148, v187
	s_add_u32 s26, s12, 0x280
	s_addc_u32 s27, s13, 0
	s_waitcnt lgkmcnt(0)
	v_add_f32_e32 v187, v187, v186
	ds_bpermute_b32 v186, v149, v187
	s_waitcnt lgkmcnt(0)
	v_add_f32_e32 v187, v187, v186
	s_and_saveexec_b64 s[28:29], s[2:3]
	global_atomic_add_f32 v147, v187, s[26:27]
	s_mov_b64 exec, s[28:29]
	s_waitcnt vmcnt(7)
	s_add_u32 s26, s72, 0xb0000
	s_addc_u32 s27, s73, 0
	s_add_u32 s28, s10, 0x58000
	s_addc_u32 s29, s11, 0
	v_pk_fma_f32 v[12:13], v[12:13], v[190:191], v[166:167]
	v_pk_fma_f32 v[14:15], v[14:15], v[192:193], v[168:169]
	global_store_dwordx4 v145, v[12:15], s[26:27]
	v_mul_f32_e32 v161, v13, v13
	v_mul_f32_e32 v186, v15, v15
	v_fmac_f32_e32 v161, v12, v12
	v_fmac_f32_e32 v186, v14, v14
	v_add_f32_e32 v187, v161, v186
	v_pk_mul_f32 v[166:167], v[206:207], v[12:13]
	v_pk_mul_f32 v[168:169], v[208:209], v[14:15]
	v_pk_mul_f32 v[166:167], v[222:223], v[166:167]
	v_pk_mul_f32 v[168:169], v[224:225], v[168:169]
	v_cvt_pk_bf16_f32 v182, v166, v167
	v_cvt_pk_bf16_f32 v183, v168, v169
	v_pk_fma_f32 v[8:9], v[8:9], v[194:195], v[170:171]
	v_pk_fma_f32 v[10:11], v[10:11], v[196:197], v[172:173]
	global_store_dwordx4 v145, v[8:11], s[26:27] offset:16
	v_mul_f32_e32 v161, v9, v9
	v_mul_f32_e32 v186, v11, v11
	v_fmac_f32_e32 v161, v8, v8
	v_fmac_f32_e32 v186, v10, v10
	v_add_f32_e32 v161, v161, v186
	v_add_f32_e32 v187, v187, v161
	v_pk_mul_f32 v[170:171], v[210:211], v[8:9]
	v_pk_mul_f32 v[172:173], v[212:213], v[10:11]
	v_pk_mul_f32 v[170:171], v[226:227], v[170:171]
	v_pk_mul_f32 v[172:173], v[228:229], v[172:173]
	v_cvt_pk_bf16_f32 v184, v170, v171
	v_cvt_pk_bf16_f32 v185, v172, v173
	global_store_dwordx4 v146, v[182:185], s[28:29]
	v_pk_fma_f32 v[4:5], v[4:5], v[198:199], v[174:175]
	v_pk_fma_f32 v[6:7], v[6:7], v[200:201], v[176:177]
	global_store_dwordx4 v145, v[4:7], s[26:27] offset:512
	v_mul_f32_e32 v161, v5, v5
	v_mul_f32_e32 v186, v7, v7
	v_fmac_f32_e32 v161, v4, v4
	v_fmac_f32_e32 v186, v6, v6
	v_add_f32_e32 v161, v161, v186
	v_add_f32_e32 v187, v187, v161
	v_pk_mul_f32 v[174:175], v[214:215], v[4:5]
	v_pk_mul_f32 v[176:177], v[216:217], v[6:7]
	v_pk_mul_f32 v[174:175], v[230:231], v[174:175]
	v_pk_mul_f32 v[176:177], v[232:233], v[176:177]
	v_cvt_pk_bf16_f32 v150, v174, v175
	v_cvt_pk_bf16_f32 v151, v176, v177
	v_pk_fma_f32 v[0:1], v[0:1], v[202:203], v[178:179]
	v_pk_fma_f32 v[2:3], v[2:3], v[204:205], v[180:181]
	global_store_dwordx4 v145, v[0:3], s[26:27] offset:528
	v_mul_f32_e32 v161, v1, v1
	v_mul_f32_e32 v186, v3, v3
	v_fmac_f32_e32 v161, v0, v0
	v_fmac_f32_e32 v186, v2, v2
	v_add_f32_e32 v161, v161, v186
	v_add_f32_e32 v187, v187, v161
	v_pk_mul_f32 v[178:179], v[218:219], v[0:1]
	v_pk_mul_f32 v[180:181], v[220:221], v[2:3]
	v_pk_mul_f32 v[178:179], v[234:235], v[178:179]
	v_pk_mul_f32 v[180:181], v[236:237], v[180:181]
	v_cvt_pk_bf16_f32 v152, v178, v179
	v_cvt_pk_bf16_f32 v153, v180, v181
	global_store_dwordx4 v146, v[150:153], s[28:29] offset:256
	ds_bpermute_b32 v186, v148, v187
	s_add_u32 s26, s12, 0x2c0
	s_addc_u32 s27, s13, 0
	s_waitcnt lgkmcnt(0)
	v_add_f32_e32 v187, v187, v186
	ds_bpermute_b32 v186, v149, v187
	s_waitcnt lgkmcnt(0)
	v_add_f32_e32 v187, v187, v186
	s_and_saveexec_b64 s[28:29], s[2:3]
	global_atomic_add_f32 v147, v187, s[26:27]
	s_mov_b64 exec, s[28:29]
	s_andn2_b64 vcc, exec, s[4:5]
	s_mov_b64 s[4:5], -1
	s_cbranch_vccnz .LBB0_583
	s_andn2_b64 vcc, exec, s[8:9]
	s_cbranch_vccnz .LBB0_582
	s_barrier
	s_branch .LBB0_582

.LBB0_764:
	s_lshr_b32 s20, s52, 5
	s_mulk_i32 s20, 0x1800
	s_ashr_i32 s21, s20, 31
	s_lshl_b64 s[20:21], s[20:21], 2
	s_add_u32 s20, s74, s20
	v_lshl_add_u32 v166, s52, 8, v148
	s_addc_u32 s21, s75, s21
	v_lshl_or_b32 v168, s53, 8, v150
	s_add_u32 s20, s20, 0xa000
	v_ashrrev_i32_e32 v167, 31, v166
	v_ashrrev_i32_e32 v169, 31, v168
	s_addc_u32 s21, s21, 0
	v_lshlrev_b64 v[146:147], 12, v[166:167]
	v_lshlrev_b64 v[170:171], 2, v[168:169]
	v_lshl_add_u64 v[144:145], s[20:21], 0, v[170:171]
	v_lshl_add_u64 v[146:147], s[72:73], 0, v[146:147]
	v_lshl_add_u64 v[146:147], v[146:147], 0, v[170:171]
	global_load_dwordx4 v[172:175], v[144:145], off
	global_load_dwordx4 v[176:179], v[144:145], off offset:16
	global_load_dwordx4 v[180:183], v[144:145], off offset:512
	global_load_dwordx4 v[184:187], v[144:145], off offset:528
	s_mov_b64 s[20:21], 0x10000
	v_lshl_add_u64 v[154:155], v[146:147], 0, s[20:21]
	s_mov_b64 s[20:21], 0x20000
	v_lshl_add_u64 v[156:157], v[146:147], 0, s[20:21]
	s_mov_b64 s[20:21], 0x30000
	v_lshl_add_u64 v[158:159], v[146:147], 0, s[20:21]
	v_lshl_add_u64 v[160:161], v[146:147], 0, s[12:13]
	v_lshl_add_u64 v[162:163], v[146:147], 0, s[14:15]
	v_lshl_add_u64 v[164:165], v[146:147], 0, s[16:17]
	v_lshl_add_u64 v[166:167], v[146:147], 0, s[4:5]
	global_load_dwordx4 v[190:193], v[146:147], off
	global_load_dwordx4 v[194:197], v[146:147], off offset:16
	global_load_dwordx4 v[198:201], v[146:147], off offset:512
	global_load_dwordx4 v[202:205], v[146:147], off offset:528
	global_load_dwordx4 v[206:209], v[154:155], off
	global_load_dwordx4 v[210:213], v[154:155], off offset:16
	global_load_dwordx4 v[214:217], v[154:155], off offset:512
	global_load_dwordx4 v[218:221], v[154:155], off offset:528
	global_load_dwordx4 v[222:225], v[156:157], off
	global_load_dwordx4 v[226:229], v[156:157], off offset:16
	global_load_dwordx4 v[230:233], v[156:157], off offset:512
	global_load_dwordx4 v[234:237], v[156:157], off offset:528
	global_load_dwordx4 v[238:241], v[158:159], off
	global_load_dwordx4 v[242:245], v[158:159], off offset:16
	global_load_dwordx4 v[246:249], v[158:159], off offset:512
	global_load_dwordx4 v[168:171], v[158:159], off offset:528
	s_waitcnt vmcnt(15)
	v_pk_fma_f32 v[124:125], v[124:125], v[172:173], v[190:191]
	v_pk_fma_f32 v[126:127], v[126:127], v[174:175], v[192:193]
	global_store_dwordx4 v[146:147], v[124:127], off
	global_load_dwordx4 v[190:193], v[160:161], off
	s_waitcnt vmcnt(16)
	v_pk_fma_f32 v[120:121], v[120:121], v[176:177], v[194:195]
	v_pk_fma_f32 v[122:123], v[122:123], v[178:179], v[196:197]
	global_store_dwordx4 v[146:147], v[120:123], off offset:16
	global_load_dwordx4 v[194:197], v[160:161], off offset:16
	s_waitcnt vmcnt(17)
	v_pk_fma_f32 v[116:117], v[116:117], v[180:181], v[198:199]
	v_pk_fma_f32 v[118:119], v[118:119], v[182:183], v[200:201]
	global_store_dwordx4 v[146:147], v[116:119], off offset:512
	global_load_dwordx4 v[198:201], v[160:161], off offset:512
	s_waitcnt vmcnt(18)
	v_pk_fma_f32 v[108:109], v[108:109], v[184:185], v[202:203]
	v_pk_fma_f32 v[110:111], v[110:111], v[186:187], v[204:205]
	global_store_dwordx4 v[146:147], v[108:111], off offset:528
	global_load_dwordx4 v[202:205], v[160:161], off offset:528
	s_waitcnt vmcnt(19)
	v_pk_fma_f32 v[112:113], v[112:113], v[172:173], v[206:207]
	v_pk_fma_f32 v[114:115], v[114:115], v[174:175], v[208:209]
	global_store_dwordx4 v[154:155], v[112:115], off
	global_load_dwordx4 v[206:209], v[162:163], off
	s_waitcnt vmcnt(20)
	v_pk_fma_f32 v[104:105], v[104:105], v[176:177], v[210:211]
	v_pk_fma_f32 v[106:107], v[106:107], v[178:179], v[212:213]
	global_store_dwordx4 v[154:155], v[104:107], off offset:16
	global_load_dwordx4 v[210:213], v[162:163], off offset:16
	s_waitcnt vmcnt(21)
	v_pk_fma_f32 v[100:101], v[100:101], v[180:181], v[214:215]
	v_pk_fma_f32 v[102:103], v[102:103], v[182:183], v[216:217]
	global_store_dwordx4 v[154:155], v[100:103], off offset:512
	global_load_dwordx4 v[214:217], v[162:163], off offset:512
	s_waitcnt vmcnt(22)
	v_pk_fma_f32 v[92:93], v[92:93], v[184:185], v[218:219]
	v_pk_fma_f32 v[94:95], v[94:95], v[186:187], v[220:221]
	global_store_dwordx4 v[154:155], v[92:95], off offset:528
	global_load_dwordx4 v[218:221], v[162:163], off offset:528
	s_waitcnt vmcnt(23)
	v_pk_fma_f32 v[96:97], v[96:97], v[172:173], v[222:223]
	v_pk_fma_f32 v[98:99], v[98:99], v[174:175], v[224:225]
	global_store_dwordx4 v[156:157], v[96:99], off
	global_load_dwordx4 v[222:225], v[164:165], off
	s_waitcnt vmcnt(24)
	v_pk_fma_f32 v[88:89], v[88:89], v[176:177], v[226:227]
	v_pk_fma_f32 v[90:91], v[90:91], v[178:179], v[228:229]
	global_store_dwordx4 v[156:157], v[88:91], off offset:16
	global_load_dwordx4 v[226:229], v[164:165], off offset:16
	s_waitcnt vmcnt(25)
	v_pk_fma_f32 v[84:85], v[84:85], v[180:181], v[230:231]
	v_pk_fma_f32 v[86:87], v[86:87], v[182:183], v[232:233]
	global_store_dwordx4 v[156:157], v[84:87], off offset:512
	global_load_dwordx4 v[230:233], v[164:165], off offset:512
	s_waitcnt vmcnt(26)
	v_pk_fma_f32 v[76:77], v[76:77], v[184:185], v[234:235]
	v_pk_fma_f32 v[78:79], v[78:79], v[186:187], v[236:237]
	global_store_dwordx4 v[156:157], v[76:79], off offset:528
	global_load_dwordx4 v[234:237], v[164:165], off offset:528
	s_waitcnt vmcnt(27)
	v_pk_fma_f32 v[80:81], v[80:81], v[172:173], v[238:239]
	v_pk_fma_f32 v[82:83], v[82:83], v[174:175], v[240:241]
	global_store_dwordx4 v[158:159], v[80:83], off
	global_load_dwordx4 v[238:241], v[166:167], off
	s_waitcnt vmcnt(28)
	v_pk_fma_f32 v[72:73], v[72:73], v[176:177], v[242:243]
	v_pk_fma_f32 v[74:75], v[74:75], v[178:179], v[244:245]
	global_store_dwordx4 v[158:159], v[72:75], off offset:16
	global_load_dwordx4 v[242:245], v[166:167], off offset:16
	s_waitcnt vmcnt(29)
	v_pk_fma_f32 v[68:69], v[68:69], v[180:181], v[246:247]
	v_pk_fma_f32 v[70:71], v[70:71], v[182:183], v[248:249]
	global_store_dwordx4 v[158:159], v[68:71], off offset:512
	global_load_dwordx4 v[246:249], v[166:167], off offset:512
	s_waitcnt vmcnt(30)
	v_pk_fma_f32 v[64:65], v[64:65], v[184:185], v[168:169]
	v_pk_fma_f32 v[66:67], v[66:67], v[186:187], v[170:171]
	global_store_dwordx4 v[158:159], v[64:67], off offset:528
	global_load_dwordx4 v[168:171], v[166:167], off offset:528
	s_waitcnt vmcnt(30)
	v_pk_fma_f32 v[60:61], v[60:61], v[172:173], v[190:191]
	v_pk_fma_f32 v[62:63], v[62:63], v[174:175], v[192:193]
	global_store_dwordx4 v[160:161], v[60:63], off
	s_waitcnt vmcnt(29)
	v_pk_fma_f32 v[56:57], v[56:57], v[176:177], v[194:195]
	v_pk_fma_f32 v[58:59], v[58:59], v[178:179], v[196:197]
	global_store_dwordx4 v[160:161], v[56:59], off offset:16
	s_waitcnt vmcnt(28)
	v_pk_fma_f32 v[52:53], v[52:53], v[180:181], v[198:199]
	v_pk_fma_f32 v[54:55], v[54:55], v[182:183], v[200:201]
	global_store_dwordx4 v[160:161], v[52:55], off offset:512
	s_waitcnt vmcnt(27)
	v_pk_fma_f32 v[48:49], v[48:49], v[184:185], v[202:203]
	v_pk_fma_f32 v[50:51], v[50:51], v[186:187], v[204:205]
	global_store_dwordx4 v[160:161], v[48:51], off offset:528
	s_waitcnt vmcnt(26)
	v_pk_fma_f32 v[44:45], v[44:45], v[172:173], v[206:207]
	v_pk_fma_f32 v[46:47], v[46:47], v[174:175], v[208:209]
	global_store_dwordx4 v[162:163], v[44:47], off
	s_waitcnt vmcnt(25)
	v_pk_fma_f32 v[40:41], v[40:41], v[176:177], v[210:211]
	v_pk_fma_f32 v[42:43], v[42:43], v[178:179], v[212:213]
	global_store_dwordx4 v[162:163], v[40:43], off offset:16
	s_waitcnt vmcnt(24)
	v_pk_fma_f32 v[36:37], v[36:37], v[180:181], v[214:215]
	v_pk_fma_f32 v[38:39], v[38:39], v[182:183], v[216:217]
	global_store_dwordx4 v[162:163], v[36:39], off offset:512
	s_waitcnt vmcnt(23)
	v_pk_fma_f32 v[32:33], v[32:33], v[184:185], v[218:219]
	v_pk_fma_f32 v[34:35], v[34:35], v[186:187], v[220:221]
	global_store_dwordx4 v[162:163], v[32:35], off offset:528
	s_waitcnt vmcnt(22)
	v_pk_fma_f32 v[28:29], v[28:29], v[172:173], v[222:223]
	v_pk_fma_f32 v[30:31], v[30:31], v[174:175], v[224:225]
	global_store_dwordx4 v[164:165], v[28:31], off
	s_waitcnt vmcnt(21)
	v_pk_fma_f32 v[24:25], v[24:25], v[176:177], v[226:227]
	v_pk_fma_f32 v[26:27], v[26:27], v[178:179], v[228:229]
	global_store_dwordx4 v[164:165], v[24:27], off offset:16
	s_waitcnt vmcnt(20)
	v_pk_fma_f32 v[20:21], v[20:21], v[180:181], v[230:231]
	v_pk_fma_f32 v[22:23], v[22:23], v[182:183], v[232:233]
	global_store_dwordx4 v[164:165], v[20:23], off offset:512
	s_waitcnt vmcnt(19)
	v_pk_fma_f32 v[16:17], v[16:17], v[184:185], v[234:235]
	v_pk_fma_f32 v[18:19], v[18:19], v[186:187], v[236:237]
	global_store_dwordx4 v[164:165], v[16:19], off offset:528
	s_waitcnt vmcnt(18)
	v_pk_fma_f32 v[12:13], v[12:13], v[172:173], v[238:239]
	v_pk_fma_f32 v[14:15], v[14:15], v[174:175], v[240:241]
	global_store_dwordx4 v[166:167], v[12:15], off
	s_waitcnt vmcnt(17)
	v_pk_fma_f32 v[8:9], v[8:9], v[176:177], v[242:243]
	v_pk_fma_f32 v[10:11], v[10:11], v[178:179], v[244:245]
	global_store_dwordx4 v[166:167], v[8:11], off offset:16
	s_waitcnt vmcnt(16)
	v_pk_fma_f32 v[4:5], v[4:5], v[180:181], v[246:247]
	v_pk_fma_f32 v[6:7], v[6:7], v[182:183], v[248:249]
	global_store_dwordx4 v[166:167], v[4:7], off offset:512
	s_waitcnt vmcnt(15)
	v_pk_fma_f32 v[0:1], v[0:1], v[184:185], v[168:169]
	v_pk_fma_f32 v[2:3], v[2:3], v[186:187], v[170:171]
	global_store_dwordx4 v[166:167], v[0:3], off offset:528
	s_and_b64 vcc, exec, s[0:1]
	s_mov_b64 s[0:1], -1
	s_cbranch_vccnz .LBB0_749
	s_andn2_b64 vcc, exec, s[6:7]
	s_cbranch_vccnz .LBB0_748
	s_barrier
	s_branch .LBB0_748
